# diff attention map-1 fast loop: K/V tile loads prefetched one tile deeper (staging registers freed by rebuilding epilogue scratch addresses), four LDS stage buffers, one barrier per key tile
# baseline (speedup 1.0000x reference)
.LBB0_789:
	s_or_b64 exec, exec, s[2:3]
	v_readlane_b32 s0, v254, 9
	s_waitcnt lgkmcnt(0)
	v_and_b32_e32 v124, 64, v230
	v_add_u32_e32 v190, 64, v124
	v_or_b32_e32 v64, s0, v241
	v_lshlrev_b32_e32 v64, 2, v64
	global_load_dword v65, v64, s[4:5]
	v_xor_b32_e32 v124, 1, v230
	v_cmp_lt_i32_e32 vcc, v124, v190
	v_lshlrev_b32_e32 v152, 1, v241
	s_movk_i32 s2, 0x100
	v_cndmask_b32_e32 v124, v230, v124, vcc
	v_lshlrev_b32_e32 v202, 2, v124
	v_xor_b32_e32 v124, 2, v230
	v_cmp_lt_i32_e32 vcc, v124, v190
	s_mov_b64 s[0:1], 0
	s_waitcnt vmcnt(0)
	v_mul_f32_e32 v131, v239, v65
	global_load_dword v65, v64, s[4:5] offset:128
	v_cndmask_b32_e32 v124, v230, v124, vcc
	v_lshlrev_b32_e32 v203, 2, v124
	v_xor_b32_e32 v124, 4, v230
	v_cmp_lt_i32_e32 vcc, v124, v190
	s_waitcnt vmcnt(0)
	v_mul_f32_e32 v130, v239, v65
	global_load_dword v65, v64, s[4:5] offset:256
	v_cndmask_b32_e32 v124, v230, v124, vcc
	global_load_dword v64, v64, s[4:5] offset:384
	v_lshlrev_b32_e32 v204, 2, v124
	v_xor_b32_e32 v124, 8, v230
	v_cmp_lt_i32_e32 vcc, v124, v190
	s_waitcnt vmcnt(1)
	v_mul_f32_e32 v129, v239, v65
	v_cndmask_b32_e32 v124, v230, v124, vcc
	s_waitcnt vmcnt(0)
	v_mul_f32_e32 v128, v239, v64
	global_load_dwordx4 v[132:135], v[144:145], off
	global_load_dwordx4 v[120:123], v[144:145], off offset:1024
	global_load_dwordx4 v[116:119], v[144:145], off offset:2048
	global_load_dwordx4 v[112:115], v[144:145], off offset:3072
	s_mov_b64 s[100:101], 0x2000
	v_lshl_add_u64 v[146:147], v[144:145], 0, s[100:101]
	s_mov_b64 s[100:101], 0x3000
	v_lshl_add_u64 v[148:149], v[144:145], 0, s[100:101]
	global_load_dwordx4 v[108:111], v[146:147], off offset:-4096
	global_load_dwordx4 v[104:107], v[146:147], off offset:-3072
	global_load_dwordx4 v[100:103], v[146:147], off offset:-2048
	global_load_dwordx4 v[96:99], v[146:147], off offset:-1024
	global_load_dwordx4 v[92:95], v[146:147], off
	global_load_dwordx4 v[88:91], v[146:147], off offset:1024
	global_load_dwordx4 v[84:87], v[146:147], off offset:2048
	global_load_dwordx4 v[80:83], v[146:147], off offset:3072
	global_load_dwordx4 v[76:79], v[148:149], off
	global_load_dwordx4 v[72:75], v[148:149], off offset:1024
	global_load_dwordx4 v[68:71], v[148:149], off offset:2048
	global_load_dwordx4 v[64:67], v[148:149], off offset:3072
	ds_read_b64 v[126:127], v240 offset:49152
	v_lshlrev_b32_e32 v205, 2, v124
	v_xor_b32_e32 v124, 16, v230
	v_cmp_lt_i32_e32 vcc, v124, v190
	s_waitcnt lgkmcnt(0)
	v_rcp_f32_e32 v126, v126
	v_cndmask_b32_e32 v124, v230, v124, vcc
	v_lshlrev_b32_e32 v206, 2, v124
	v_lshlrev_b32_e32 v124, 5, v243
	v_mul_f32_e32 v126, s20, v126
	v_ashrrev_i32_e32 v125, 31, v124
	v_lshl_add_u64 v[124:125], v[124:125], 0, s[8:9]
	v_lshl_or_b32 v124, v242, 2, v124
	s_and_b64 vcc, exec, s[6:7]
	s_waitcnt vmcnt(15)
	v_fma_f32 v32, -v32, v126, v133
	v_fma_f32 v48, -v48, v126, v132
	v_mul_f32_e32 v132, v32, v32
	v_fmac_f32_e32 v132, v48, v48
	v_fma_f32 v16, -v16, v126, v134
	v_fmac_f32_e32 v132, v16, v16
	v_fma_f32 v0, -v0, v126, v135
	v_fmac_f32_e32 v132, v0, v0
	ds_bpermute_b32 v126, v202, v132
	s_waitcnt lgkmcnt(0)
	v_add_f32_e32 v126, v132, v126
	ds_bpermute_b32 v132, v203, v126
	s_waitcnt lgkmcnt(0)
	v_add_f32_e32 v126, v126, v132
	ds_bpermute_b32 v132, v204, v126
	s_waitcnt lgkmcnt(0)
	v_add_f32_e32 v126, v126, v132
	ds_bpermute_b32 v132, v205, v126
	s_waitcnt lgkmcnt(0)
	v_add_f32_e32 v126, v126, v132
	ds_bpermute_b32 v132, v206, v126
	s_waitcnt lgkmcnt(0)
	v_add_f32_e32 v126, v126, v132
	v_fmamk_f32 v126, v126, 0x3c000000, v228
	v_rsq_f32_e32 v126, v126
	v_lshlrev_b64 v[132:133], 11, v[124:125]
	v_lshl_add_u64 v[132:133], s[42:43], 0, v[132:133]
	v_lshl_add_u64 v[132:133], v[132:133], 0, v[152:153]
	v_mul_f32_e32 v48, v48, v126
	v_mul_f32_e32 v48, v131, v48
	v_bfe_u32 v134, v48, 16, 1
	v_mul_f32_e32 v32, v32, v126
	v_add3_u32 v48, v48, v134, s96
	v_mul_f32_e32 v32, v130, v32
	global_store_short_d16_hi v[132:133], v48, off offset:512
	v_bfe_u32 v48, v32, 16, 1
	v_mul_f32_e32 v16, v16, v126
	v_add3_u32 v32, v32, v48, s96
	v_mul_f32_e32 v16, v129, v16
	global_store_short_d16_hi v[132:133], v32, off offset:576
	v_bfe_u32 v32, v16, 16, 1
	v_mul_f32_e32 v0, v0, v126
	v_add3_u32 v16, v16, v32, s96
	v_mul_f32_e32 v0, v128, v0
	global_store_short_d16_hi v[132:133], v16, off offset:640
	v_bfe_u32 v16, v0, 16, 1
	v_add3_u32 v0, v0, v16, s96
	global_store_short_d16_hi v[132:133], v0, off offset:704
	v_rcp_f32_e32 v0, v127
	s_nop 0
	v_mul_f32_e32 v0, s20, v0
	s_waitcnt vmcnt(18)
	v_fma_f32 v32, -v33, v0, v121
	v_fma_f32 v48, -v49, v0, v120
	v_mul_f32_e32 v33, v32, v32
	v_fmac_f32_e32 v33, v48, v48
	v_fma_f32 v17, -v17, v0, v122
	v_fmac_f32_e32 v33, v17, v17
	v_fma_f32 v16, -v1, v0, v123
	v_fmac_f32_e32 v33, v16, v16
	ds_bpermute_b32 v0, v202, v33
	s_waitcnt lgkmcnt(0)
	v_add_f32_e32 v0, v33, v0
	ds_bpermute_b32 v1, v203, v0
	s_waitcnt lgkmcnt(0)
	v_add_f32_e32 v0, v0, v1
	ds_bpermute_b32 v1, v204, v0
	s_waitcnt lgkmcnt(0)
	v_add_f32_e32 v0, v0, v1
	ds_bpermute_b32 v1, v205, v0
	s_waitcnt lgkmcnt(0)
	v_add_f32_e32 v0, v0, v1
	ds_bpermute_b32 v1, v206, v0
	s_waitcnt lgkmcnt(0)
	v_add_f32_e32 v0, v0, v1
	v_fmamk_f32 v0, v0, 0x3c000000, v228
	v_rsq_f32_e32 v33, v0
	v_or_b32_e32 v0, 1, v124
	v_mov_b32_e32 v1, v125
	v_lshlrev_b64 v[0:1], 11, v[0:1]
	v_mul_f32_e32 v48, v48, v33
	v_mul_f32_e32 v48, v131, v48
	v_lshl_add_u64 v[0:1], s[42:43], 0, v[0:1]
	v_bfe_u32 v49, v48, 16, 1
	v_mul_f32_e32 v32, v32, v33
	v_lshl_add_u64 v[0:1], v[0:1], 0, v[152:153]
	v_add3_u32 v48, v48, v49, s96
	v_mul_f32_e32 v32, v130, v32
	global_store_short_d16_hi v[0:1], v48, off offset:512
	v_bfe_u32 v48, v32, 16, 1
	v_mul_f32_e32 v17, v17, v33
	v_add3_u32 v32, v32, v48, s96
	v_mul_f32_e32 v17, v129, v17
	global_store_short_d16_hi v[0:1], v32, off offset:576
	v_bfe_u32 v32, v17, 16, 1
	v_mul_f32_e32 v16, v16, v33
	v_add3_u32 v17, v17, v32, s96
	v_mul_f32_e32 v16, v128, v16
	global_store_short_d16_hi v[0:1], v17, off offset:640
	v_bfe_u32 v17, v16, 16, 1
	v_add3_u32 v16, v16, v17, s96
	global_store_short_d16_hi v[0:1], v16, off offset:704
	ds_read_b64 v[0:1], v240 offset:49160
	v_mov_b32_e32 v17, v125
	s_waitcnt lgkmcnt(0)
	v_rcp_f32_e32 v0, v0
	s_nop 0
	v_mul_f32_e32 v0, s20, v0
	s_waitcnt vmcnt(21)
	v_fma_f32 v33, -v34, v0, v117
	v_fma_f32 v32, -v50, v0, v116
	v_mul_f32_e32 v16, v33, v33
	v_fmac_f32_e32 v16, v32, v32
	v_fma_f32 v18, -v18, v0, v118
	v_fmac_f32_e32 v16, v18, v18
	v_fma_f32 v0, -v2, v0, v119
	v_fmac_f32_e32 v16, v0, v0
	ds_bpermute_b32 v2, v202, v16
	s_waitcnt lgkmcnt(0)
	v_add_f32_e32 v2, v16, v2
	ds_bpermute_b32 v16, v203, v2
	s_waitcnt lgkmcnt(0)
	v_add_f32_e32 v2, v2, v16
	ds_bpermute_b32 v16, v204, v2
	s_waitcnt lgkmcnt(0)
	v_add_f32_e32 v2, v2, v16
	ds_bpermute_b32 v16, v205, v2
	s_waitcnt lgkmcnt(0)
	v_add_f32_e32 v2, v2, v16
	ds_bpermute_b32 v16, v206, v2
	s_waitcnt lgkmcnt(0)
	v_add_f32_e32 v2, v2, v16
	v_fmamk_f32 v2, v2, 0x3c000000, v228
	v_rsq_f32_e32 v2, v2
	v_or_b32_e32 v16, 2, v124
	v_lshlrev_b64 v[16:17], 11, v[16:17]
	v_lshl_add_u64 v[16:17], s[42:43], 0, v[16:17]
	v_mul_f32_e32 v32, v32, v2
	v_mul_f32_e32 v32, v131, v32
	v_bfe_u32 v34, v32, 16, 1
	v_mul_f32_e32 v0, v0, v2
	v_lshl_add_u64 v[16:17], v[16:17], 0, v[152:153]
	v_add3_u32 v32, v32, v34, s96
	v_mul_f32_e32 v0, v128, v0
	global_store_short_d16_hi v[16:17], v32, off offset:512
	v_mul_f32_e32 v32, v33, v2
	v_mul_f32_e32 v18, v18, v2
	v_bfe_u32 v2, v0, 16, 1
	v_add3_u32 v0, v0, v2, s96
	v_mul_f32_e32 v32, v130, v32
	global_store_short_d16_hi v[16:17], v0, off offset:704
	v_rcp_f32_e32 v0, v1
	v_bfe_u32 v33, v32, 16, 1
	v_add3_u32 v32, v32, v33, s96
	v_mul_f32_e32 v18, v129, v18
	global_store_short_d16_hi v[16:17], v32, off offset:576
	v_bfe_u32 v32, v18, 16, 1
	v_add3_u32 v18, v18, v32, s96
	v_mul_f32_e32 v0, s20, v0
	global_store_short_d16_hi v[16:17], v18, off offset:640
	s_waitcnt vmcnt(24)
	v_fma_f32 v16, -v35, v0, v113
	v_fma_f32 v2, -v51, v0, v112
	v_mul_f32_e32 v1, v16, v16
	v_fmac_f32_e32 v1, v2, v2
	v_fma_f32 v17, -v19, v0, v114
	v_fmac_f32_e32 v1, v17, v17
	v_fma_f32 v3, -v3, v0, v115
	v_fmac_f32_e32 v1, v3, v3
	ds_bpermute_b32 v0, v202, v1
	s_waitcnt lgkmcnt(0)
	v_add_f32_e32 v0, v1, v0
	ds_bpermute_b32 v1, v203, v0
	s_waitcnt lgkmcnt(0)
	v_add_f32_e32 v0, v0, v1
	ds_bpermute_b32 v1, v204, v0
	s_waitcnt lgkmcnt(0)
	v_add_f32_e32 v0, v0, v1
	ds_bpermute_b32 v1, v205, v0
	s_waitcnt lgkmcnt(0)
	v_add_f32_e32 v0, v0, v1
	ds_bpermute_b32 v1, v206, v0
	s_waitcnt lgkmcnt(0)
	v_add_f32_e32 v0, v0, v1
	v_fmamk_f32 v0, v0, 0x3c000000, v228
	v_rsq_f32_e32 v18, v0
	v_or_b32_e32 v0, 3, v124
	v_mov_b32_e32 v1, v125
	v_lshlrev_b64 v[0:1], 11, v[0:1]
	v_mul_f32_e32 v2, v2, v18
	v_mul_f32_e32 v2, v131, v2
	v_lshl_add_u64 v[0:1], s[42:43], 0, v[0:1]
	v_bfe_u32 v19, v2, 16, 1
	v_lshl_add_u64 v[0:1], v[0:1], 0, v[152:153]
	v_add3_u32 v2, v2, v19, s96
	global_store_short_d16_hi v[0:1], v2, off offset:512
	v_mul_f32_e32 v2, v16, v18
	v_mul_f32_e32 v2, v130, v2
	v_bfe_u32 v16, v2, 16, 1
	v_add3_u32 v2, v2, v16, s96
	global_store_short_d16_hi v[0:1], v2, off offset:576
	v_mul_f32_e32 v2, v17, v18
	v_mul_f32_e32 v2, v129, v2
	v_bfe_u32 v16, v2, 16, 1
	v_add3_u32 v2, v2, v16, s96
	global_store_short_d16_hi v[0:1], v2, off offset:640
	v_mul_f32_e32 v2, v3, v18
	v_mul_f32_e32 v2, v128, v2
	v_bfe_u32 v3, v2, 16, 1
	v_add3_u32 v2, v2, v3, s96
	global_store_short_d16_hi v[0:1], v2, off offset:704
	ds_read_b64 v[0:1], v240 offset:49184
	s_waitcnt lgkmcnt(0)
	v_rcp_f32_e32 v0, v0
	s_nop 0
	v_mul_f32_e32 v0, s20, v0
	s_waitcnt vmcnt(27)
	v_fma_f32 v17, -v36, v0, v109
	v_fma_f32 v16, -v52, v0, v108
	v_mul_f32_e32 v2, v17, v17
	v_fmac_f32_e32 v2, v16, v16
	v_fma_f32 v18, -v20, v0, v110
	v_fmac_f32_e32 v2, v18, v18
	v_fma_f32 v0, -v4, v0, v111
	v_fmac_f32_e32 v2, v0, v0
	ds_bpermute_b32 v3, v202, v2
	s_waitcnt lgkmcnt(0)
	v_add_f32_e32 v2, v2, v3
	ds_bpermute_b32 v3, v203, v2
	s_waitcnt lgkmcnt(0)
	v_add_f32_e32 v2, v2, v3
	ds_bpermute_b32 v3, v204, v2
	s_waitcnt lgkmcnt(0)
	v_add_f32_e32 v2, v2, v3
	ds_bpermute_b32 v3, v205, v2
	s_waitcnt lgkmcnt(0)
	v_add_f32_e32 v2, v2, v3
	ds_bpermute_b32 v3, v206, v2
	s_waitcnt lgkmcnt(0)
	v_add_f32_e32 v2, v2, v3
	v_fmamk_f32 v2, v2, 0x3c000000, v228
	v_rsq_f32_e32 v4, v2
	v_or_b32_e32 v2, 8, v124
	v_mov_b32_e32 v3, v125
	v_lshlrev_b64 v[2:3], 11, v[2:3]
	v_mul_f32_e32 v16, v16, v4
	v_mul_f32_e32 v16, v131, v16
	v_lshl_add_u64 v[2:3], s[42:43], 0, v[2:3]
	v_bfe_u32 v19, v16, 16, 1
	v_lshl_add_u64 v[2:3], v[2:3], 0, v[152:153]
	v_add3_u32 v16, v16, v19, s96
	global_store_short_d16_hi v[2:3], v16, off offset:512
	v_mul_f32_e32 v16, v17, v4
	v_mul_f32_e32 v16, v130, v16
	v_bfe_u32 v17, v16, 16, 1
	v_mul_f32_e32 v0, v0, v4
	v_add3_u32 v16, v16, v17, s96
	v_mul_f32_e32 v0, v128, v0
	global_store_short_d16_hi v[2:3], v16, off offset:576
	v_mul_f32_e32 v16, v18, v4
	v_bfe_u32 v4, v0, 16, 1
	v_add3_u32 v0, v0, v4, s96
	global_store_short_d16_hi v[2:3], v0, off offset:704
	v_rcp_f32_e32 v0, v1
	v_mul_f32_e32 v16, v129, v16
	v_bfe_u32 v17, v16, 16, 1
	v_add3_u32 v16, v16, v17, s96
	v_mul_f32_e32 v0, s20, v0
	global_store_short_d16_hi v[2:3], v16, off offset:640
	s_waitcnt vmcnt(30)
	v_fma_f32 v3, -v37, v0, v105
	v_fma_f32 v2, -v53, v0, v104
	v_mul_f32_e32 v1, v3, v3
	v_fmac_f32_e32 v1, v2, v2
	v_fma_f32 v4, -v21, v0, v106
	v_fmac_f32_e32 v1, v4, v4
	v_fma_f32 v5, -v5, v0, v107
	v_fmac_f32_e32 v1, v5, v5
	ds_bpermute_b32 v0, v202, v1
	s_waitcnt lgkmcnt(0)
	v_add_f32_e32 v0, v1, v0
	ds_bpermute_b32 v1, v203, v0
	s_waitcnt lgkmcnt(0)
	v_add_f32_e32 v0, v0, v1
	ds_bpermute_b32 v1, v204, v0
	s_waitcnt lgkmcnt(0)
	v_add_f32_e32 v0, v0, v1
	ds_bpermute_b32 v1, v205, v0
	s_waitcnt lgkmcnt(0)
	v_add_f32_e32 v0, v0, v1
	ds_bpermute_b32 v1, v206, v0
	s_waitcnt lgkmcnt(0)
	v_add_f32_e32 v0, v0, v1
	v_fmamk_f32 v0, v0, 0x3c000000, v228
	v_rsq_f32_e32 v16, v0
	v_or_b32_e32 v0, 9, v124
	v_mov_b32_e32 v1, v125
	v_lshlrev_b64 v[0:1], 11, v[0:1]
	v_mul_f32_e32 v2, v2, v16
	v_mul_f32_e32 v2, v131, v2
	v_lshl_add_u64 v[0:1], s[42:43], 0, v[0:1]
	v_bfe_u32 v17, v2, 16, 1
	v_lshl_add_u64 v[0:1], v[0:1], 0, v[152:153]
	v_add3_u32 v2, v2, v17, s96
	global_store_short_d16_hi v[0:1], v2, off offset:512
	v_mul_f32_e32 v2, v3, v16
	v_mul_f32_e32 v2, v130, v2
	v_bfe_u32 v3, v2, 16, 1
	v_add3_u32 v2, v2, v3, s96
	global_store_short_d16_hi v[0:1], v2, off offset:576
	v_mul_f32_e32 v2, v4, v16
	v_mul_f32_e32 v2, v129, v2
	v_bfe_u32 v3, v2, 16, 1
	v_add3_u32 v2, v2, v3, s96
	global_store_short_d16_hi v[0:1], v2, off offset:640
	v_mul_f32_e32 v2, v5, v16
	v_mul_f32_e32 v2, v128, v2
	v_bfe_u32 v3, v2, 16, 1
	v_add3_u32 v2, v2, v3, s96
	global_store_short_d16_hi v[0:1], v2, off offset:704
	ds_read_b64 v[0:1], v240 offset:49192
	s_waitcnt lgkmcnt(0)
	v_rcp_f32_e32 v0, v0
	s_nop 0
	v_mul_f32_e32 v0, s20, v0
	s_waitcnt vmcnt(33)
	v_fma_f32 v5, -v38, v0, v101
	v_fma_f32 v4, -v54, v0, v100
	v_mul_f32_e32 v2, v5, v5
	v_fmac_f32_e32 v2, v4, v4
	v_fma_f32 v16, -v22, v0, v102
	v_fmac_f32_e32 v2, v16, v16
	v_fma_f32 v0, -v6, v0, v103
	v_fmac_f32_e32 v2, v0, v0
	ds_bpermute_b32 v3, v202, v2
	s_waitcnt lgkmcnt(0)
	v_add_f32_e32 v2, v2, v3
	ds_bpermute_b32 v3, v203, v2
	s_waitcnt lgkmcnt(0)
	v_add_f32_e32 v2, v2, v3
	ds_bpermute_b32 v3, v204, v2
	s_waitcnt lgkmcnt(0)
	v_add_f32_e32 v2, v2, v3
	ds_bpermute_b32 v3, v205, v2
	s_waitcnt lgkmcnt(0)
	v_add_f32_e32 v2, v2, v3
	ds_bpermute_b32 v3, v206, v2
	s_waitcnt lgkmcnt(0)
	v_add_f32_e32 v2, v2, v3
	v_fmamk_f32 v2, v2, 0x3c000000, v228
	v_rsq_f32_e32 v6, v2
	v_or_b32_e32 v2, 10, v124
	v_mov_b32_e32 v3, v125
	v_lshlrev_b64 v[2:3], 11, v[2:3]
	v_mul_f32_e32 v4, v4, v6
	v_mul_f32_e32 v4, v131, v4
	v_lshl_add_u64 v[2:3], s[42:43], 0, v[2:3]
	v_bfe_u32 v17, v4, 16, 1
	v_lshl_add_u64 v[2:3], v[2:3], 0, v[152:153]
	v_add3_u32 v4, v4, v17, s96
	global_store_short_d16_hi v[2:3], v4, off offset:512
	v_mul_f32_e32 v4, v5, v6
	v_mul_f32_e32 v4, v130, v4
	v_bfe_u32 v5, v4, 16, 1
	v_add3_u32 v4, v4, v5, s96
	global_store_short_d16_hi v[2:3], v4, off offset:576
	v_mul_f32_e32 v4, v16, v6
	v_mul_f32_e32 v4, v129, v4
	v_bfe_u32 v5, v4, 16, 1
	v_mul_f32_e32 v0, v0, v6
	v_add3_u32 v4, v4, v5, s96
	v_mul_f32_e32 v0, v128, v0
	global_store_short_d16_hi v[2:3], v4, off offset:640
	v_bfe_u32 v4, v0, 16, 1
	v_add3_u32 v0, v0, v4, s96
	global_store_short_d16_hi v[2:3], v0, off offset:704
	v_rcp_f32_e32 v0, v1
	s_nop 0
	v_mul_f32_e32 v0, s20, v0
	s_waitcnt vmcnt(36)
	v_fma_f32 v3, -v39, v0, v97
	v_fma_f32 v2, -v55, v0, v96
	v_mul_f32_e32 v1, v3, v3
	v_fmac_f32_e32 v1, v2, v2
	v_fma_f32 v4, -v23, v0, v98
	v_fmac_f32_e32 v1, v4, v4
	v_fma_f32 v5, -v7, v0, v99
	v_fmac_f32_e32 v1, v5, v5
	ds_bpermute_b32 v0, v202, v1
	s_waitcnt lgkmcnt(0)
	v_add_f32_e32 v0, v1, v0
	ds_bpermute_b32 v1, v203, v0
	s_waitcnt lgkmcnt(0)
	v_add_f32_e32 v0, v0, v1
	ds_bpermute_b32 v1, v204, v0
	s_waitcnt lgkmcnt(0)
	v_add_f32_e32 v0, v0, v1
	ds_bpermute_b32 v1, v205, v0
	s_waitcnt lgkmcnt(0)
	v_add_f32_e32 v0, v0, v1
	ds_bpermute_b32 v1, v206, v0
	s_waitcnt lgkmcnt(0)
	v_add_f32_e32 v0, v0, v1
	v_fmamk_f32 v0, v0, 0x3c000000, v228
	v_rsq_f32_e32 v6, v0
	v_or_b32_e32 v0, 11, v124
	v_mov_b32_e32 v1, v125
	v_lshlrev_b64 v[0:1], 11, v[0:1]
	v_mul_f32_e32 v2, v2, v6
	v_mul_f32_e32 v2, v131, v2
	v_lshl_add_u64 v[0:1], s[42:43], 0, v[0:1]
	v_bfe_u32 v7, v2, 16, 1
	v_lshl_add_u64 v[0:1], v[0:1], 0, v[152:153]
	v_add3_u32 v2, v2, v7, s96
	global_store_short_d16_hi v[0:1], v2, off offset:512
	v_mul_f32_e32 v2, v3, v6
	v_mul_f32_e32 v2, v130, v2
	v_bfe_u32 v3, v2, 16, 1
	v_add3_u32 v2, v2, v3, s96
	global_store_short_d16_hi v[0:1], v2, off offset:576
	v_mul_f32_e32 v2, v4, v6
	v_mul_f32_e32 v2, v129, v2
	v_bfe_u32 v3, v2, 16, 1
	v_add3_u32 v2, v2, v3, s96
	global_store_short_d16_hi v[0:1], v2, off offset:640
	v_mul_f32_e32 v2, v5, v6
	v_mul_f32_e32 v2, v128, v2
	v_bfe_u32 v3, v2, 16, 1
	v_add3_u32 v2, v2, v3, s96
	global_store_short_d16_hi v[0:1], v2, off offset:704
	ds_read_b64 v[0:1], v240 offset:49216
	s_waitcnt lgkmcnt(0)
	v_rcp_f32_e32 v0, v0
	s_nop 0
	v_mul_f32_e32 v0, s20, v0
	s_waitcnt vmcnt(39)
	v_fma_f32 v5, -v40, v0, v93
	v_fma_f32 v4, -v56, v0, v92
	v_mul_f32_e32 v2, v5, v5
	v_fmac_f32_e32 v2, v4, v4
	v_fma_f32 v6, -v24, v0, v94
	v_fmac_f32_e32 v2, v6, v6
	v_fma_f32 v0, -v8, v0, v95
	v_fmac_f32_e32 v2, v0, v0
	ds_bpermute_b32 v3, v202, v2
	s_waitcnt lgkmcnt(0)
	v_add_f32_e32 v2, v2, v3
	ds_bpermute_b32 v3, v203, v2
	s_waitcnt lgkmcnt(0)
	v_add_f32_e32 v2, v2, v3
	ds_bpermute_b32 v3, v204, v2
	s_waitcnt lgkmcnt(0)
	v_add_f32_e32 v2, v2, v3
	ds_bpermute_b32 v3, v205, v2
	s_waitcnt lgkmcnt(0)
	v_add_f32_e32 v2, v2, v3
	ds_bpermute_b32 v3, v206, v2
	s_waitcnt lgkmcnt(0)
	v_add_f32_e32 v2, v2, v3
	v_fmamk_f32 v2, v2, 0x3c000000, v228
	v_rsq_f32_e32 v7, v2
	v_or_b32_e32 v2, 16, v124
	v_mov_b32_e32 v3, v125
	v_lshlrev_b64 v[2:3], 11, v[2:3]
	v_mul_f32_e32 v4, v4, v7
	v_mul_f32_e32 v4, v131, v4
	v_lshl_add_u64 v[2:3], s[42:43], 0, v[2:3]
	v_bfe_u32 v8, v4, 16, 1
	v_lshl_add_u64 v[2:3], v[2:3], 0, v[152:153]
	v_add3_u32 v4, v4, v8, s96
	global_store_short_d16_hi v[2:3], v4, off offset:512
	v_mul_f32_e32 v4, v5, v7
	v_mul_f32_e32 v4, v130, v4
	v_bfe_u32 v5, v4, 16, 1
	v_add3_u32 v4, v4, v5, s96
	global_store_short_d16_hi v[2:3], v4, off offset:576
	v_mul_f32_e32 v4, v6, v7
	v_mul_f32_e32 v4, v129, v4
	v_bfe_u32 v5, v4, 16, 1
	v_mul_f32_e32 v0, v0, v7
	v_add3_u32 v4, v4, v5, s96
	v_mul_f32_e32 v0, v128, v0
	global_store_short_d16_hi v[2:3], v4, off offset:640
	v_bfe_u32 v4, v0, 16, 1
	v_add3_u32 v0, v0, v4, s96
	global_store_short_d16_hi v[2:3], v0, off offset:704
	v_rcp_f32_e32 v0, v1
	s_nop 0
	v_mul_f32_e32 v0, s20, v0
	s_waitcnt vmcnt(42)
	v_fma_f32 v3, -v41, v0, v89
	v_fma_f32 v2, -v57, v0, v88
	v_mul_f32_e32 v1, v3, v3
	v_fmac_f32_e32 v1, v2, v2
	v_fma_f32 v4, -v25, v0, v90
	v_fmac_f32_e32 v1, v4, v4
	v_fma_f32 v5, -v9, v0, v91
	v_fmac_f32_e32 v1, v5, v5
	ds_bpermute_b32 v0, v202, v1
	s_waitcnt lgkmcnt(0)
	v_add_f32_e32 v0, v1, v0
	ds_bpermute_b32 v1, v203, v0
	s_waitcnt lgkmcnt(0)
	v_add_f32_e32 v0, v0, v1
	ds_bpermute_b32 v1, v204, v0
	s_waitcnt lgkmcnt(0)
	v_add_f32_e32 v0, v0, v1
	ds_bpermute_b32 v1, v205, v0
	s_waitcnt lgkmcnt(0)
	v_add_f32_e32 v0, v0, v1
	ds_bpermute_b32 v1, v206, v0
	s_waitcnt lgkmcnt(0)
	v_add_f32_e32 v0, v0, v1
	v_fmamk_f32 v0, v0, 0x3c000000, v228
	v_rsq_f32_e32 v6, v0
	v_or_b32_e32 v0, 17, v124
	v_mov_b32_e32 v1, v125
	v_lshlrev_b64 v[0:1], 11, v[0:1]
	v_mul_f32_e32 v2, v2, v6
	v_mul_f32_e32 v2, v131, v2
	v_lshl_add_u64 v[0:1], s[42:43], 0, v[0:1]
	v_bfe_u32 v7, v2, 16, 1
	v_lshl_add_u64 v[0:1], v[0:1], 0, v[152:153]
	v_add3_u32 v2, v2, v7, s96
	global_store_short_d16_hi v[0:1], v2, off offset:512
	v_mul_f32_e32 v2, v3, v6
	v_mul_f32_e32 v2, v130, v2
	v_bfe_u32 v3, v2, 16, 1
	v_add3_u32 v2, v2, v3, s96
	global_store_short_d16_hi v[0:1], v2, off offset:576
	v_mul_f32_e32 v2, v4, v6
	v_mul_f32_e32 v2, v129, v2
	v_bfe_u32 v3, v2, 16, 1
	v_add3_u32 v2, v2, v3, s96
	global_store_short_d16_hi v[0:1], v2, off offset:640
	v_mul_f32_e32 v2, v5, v6
	v_mul_f32_e32 v2, v128, v2
	v_bfe_u32 v3, v2, 16, 1
	v_add3_u32 v2, v2, v3, s96
	global_store_short_d16_hi v[0:1], v2, off offset:704
	ds_read_b64 v[0:1], v240 offset:49224
	s_waitcnt lgkmcnt(0)
	v_rcp_f32_e32 v0, v0
	s_nop 0
	v_mul_f32_e32 v0, s20, v0
	s_waitcnt vmcnt(45)
	v_fma_f32 v5, -v42, v0, v85
	v_fma_f32 v4, -v58, v0, v84
	v_mul_f32_e32 v2, v5, v5
	v_fmac_f32_e32 v2, v4, v4
	v_fma_f32 v6, -v26, v0, v86
	v_fmac_f32_e32 v2, v6, v6
	v_fma_f32 v0, -v10, v0, v87
	v_fmac_f32_e32 v2, v0, v0
	ds_bpermute_b32 v3, v202, v2
	s_waitcnt lgkmcnt(0)
	v_add_f32_e32 v2, v2, v3
	ds_bpermute_b32 v3, v203, v2
	s_waitcnt lgkmcnt(0)
	v_add_f32_e32 v2, v2, v3
	ds_bpermute_b32 v3, v204, v2
	s_waitcnt lgkmcnt(0)
	v_add_f32_e32 v2, v2, v3
	ds_bpermute_b32 v3, v205, v2
	s_waitcnt lgkmcnt(0)
	v_add_f32_e32 v2, v2, v3
	ds_bpermute_b32 v3, v206, v2
	s_waitcnt lgkmcnt(0)
	v_add_f32_e32 v2, v2, v3
	v_fmamk_f32 v2, v2, 0x3c000000, v228
	v_rsq_f32_e32 v7, v2
	v_or_b32_e32 v2, 18, v124
	v_mov_b32_e32 v3, v125
	v_lshlrev_b64 v[2:3], 11, v[2:3]
	v_mul_f32_e32 v4, v4, v7
	v_mul_f32_e32 v4, v131, v4
	v_lshl_add_u64 v[2:3], s[42:43], 0, v[2:3]
	v_bfe_u32 v8, v4, 16, 1
	v_lshl_add_u64 v[2:3], v[2:3], 0, v[152:153]
	v_add3_u32 v4, v4, v8, s96
	global_store_short_d16_hi v[2:3], v4, off offset:512
	v_mul_f32_e32 v4, v5, v7
	v_mul_f32_e32 v4, v130, v4
	v_bfe_u32 v5, v4, 16, 1
	v_add3_u32 v4, v4, v5, s96
	global_store_short_d16_hi v[2:3], v4, off offset:576
	v_mul_f32_e32 v4, v6, v7
	v_mul_f32_e32 v4, v129, v4
	v_bfe_u32 v5, v4, 16, 1
	v_mul_f32_e32 v0, v0, v7
	v_add3_u32 v4, v4, v5, s96
	v_mul_f32_e32 v0, v128, v0
	global_store_short_d16_hi v[2:3], v4, off offset:640
	v_bfe_u32 v4, v0, 16, 1
	v_add3_u32 v0, v0, v4, s96
	global_store_short_d16_hi v[2:3], v0, off offset:704
	v_rcp_f32_e32 v0, v1
	s_nop 0
	v_mul_f32_e32 v0, s20, v0
	s_waitcnt vmcnt(48)
	v_fma_f32 v3, -v43, v0, v81
	v_fma_f32 v2, -v59, v0, v80
	v_mul_f32_e32 v1, v3, v3
	v_fmac_f32_e32 v1, v2, v2
	v_fma_f32 v4, -v27, v0, v82
	v_fmac_f32_e32 v1, v4, v4
	v_fma_f32 v5, -v11, v0, v83
	v_fmac_f32_e32 v1, v5, v5
	ds_bpermute_b32 v0, v202, v1
	s_waitcnt lgkmcnt(0)
	v_add_f32_e32 v0, v1, v0
	ds_bpermute_b32 v1, v203, v0
	s_waitcnt lgkmcnt(0)
	v_add_f32_e32 v0, v0, v1
	ds_bpermute_b32 v1, v204, v0
	s_waitcnt lgkmcnt(0)
	v_add_f32_e32 v0, v0, v1
	ds_bpermute_b32 v1, v205, v0
	s_waitcnt lgkmcnt(0)
	v_add_f32_e32 v0, v0, v1
	ds_bpermute_b32 v1, v206, v0
	s_waitcnt lgkmcnt(0)
	v_add_f32_e32 v0, v0, v1
	v_fmamk_f32 v0, v0, 0x3c000000, v228
	v_rsq_f32_e32 v6, v0
	v_or_b32_e32 v0, 19, v124
	v_mov_b32_e32 v1, v125
	v_lshlrev_b64 v[0:1], 11, v[0:1]
	v_mul_f32_e32 v2, v2, v6
	v_mul_f32_e32 v2, v131, v2
	v_lshl_add_u64 v[0:1], s[42:43], 0, v[0:1]
	v_bfe_u32 v7, v2, 16, 1
	v_lshl_add_u64 v[0:1], v[0:1], 0, v[152:153]
	v_add3_u32 v2, v2, v7, s96
	global_store_short_d16_hi v[0:1], v2, off offset:512
	v_mul_f32_e32 v2, v3, v6
	v_mul_f32_e32 v2, v130, v2
	v_bfe_u32 v3, v2, 16, 1
	v_add3_u32 v2, v2, v3, s96
	global_store_short_d16_hi v[0:1], v2, off offset:576
	v_mul_f32_e32 v2, v4, v6
	v_mul_f32_e32 v2, v129, v2
	v_bfe_u32 v3, v2, 16, 1
	v_add3_u32 v2, v2, v3, s96
	global_store_short_d16_hi v[0:1], v2, off offset:640
	v_mul_f32_e32 v2, v5, v6
	v_mul_f32_e32 v2, v128, v2
	v_bfe_u32 v3, v2, 16, 1
	v_add3_u32 v2, v2, v3, s96
	global_store_short_d16_hi v[0:1], v2, off offset:704
	ds_read_b64 v[0:1], v240 offset:49248
	s_waitcnt lgkmcnt(0)
	v_rcp_f32_e32 v0, v0
	s_nop 0
	v_mul_f32_e32 v0, s20, v0
	s_waitcnt vmcnt(51)
	v_fma_f32 v5, -v44, v0, v77
	v_fma_f32 v4, -v60, v0, v76
	v_mul_f32_e32 v2, v5, v5
	v_fmac_f32_e32 v2, v4, v4
	v_fma_f32 v6, -v28, v0, v78
	v_fmac_f32_e32 v2, v6, v6
	v_fma_f32 v0, -v12, v0, v79
	v_fmac_f32_e32 v2, v0, v0
	ds_bpermute_b32 v3, v202, v2
	s_waitcnt lgkmcnt(0)
	v_add_f32_e32 v2, v2, v3
	ds_bpermute_b32 v3, v203, v2
	s_waitcnt lgkmcnt(0)
	v_add_f32_e32 v2, v2, v3
	ds_bpermute_b32 v3, v204, v2
	s_waitcnt lgkmcnt(0)
	v_add_f32_e32 v2, v2, v3
	ds_bpermute_b32 v3, v205, v2
	s_waitcnt lgkmcnt(0)
	v_add_f32_e32 v2, v2, v3
	ds_bpermute_b32 v3, v206, v2
	s_waitcnt lgkmcnt(0)
	v_add_f32_e32 v2, v2, v3
	v_fmamk_f32 v2, v2, 0x3c000000, v228
	v_rsq_f32_e32 v7, v2
	v_or_b32_e32 v2, 24, v124
	v_mov_b32_e32 v3, v125
	v_lshlrev_b64 v[2:3], 11, v[2:3]
	v_mul_f32_e32 v4, v4, v7
	v_mul_f32_e32 v4, v131, v4
	v_lshl_add_u64 v[2:3], s[42:43], 0, v[2:3]
	v_bfe_u32 v8, v4, 16, 1
	v_lshl_add_u64 v[2:3], v[2:3], 0, v[152:153]
	v_add3_u32 v4, v4, v8, s96
	global_store_short_d16_hi v[2:3], v4, off offset:512
	v_mul_f32_e32 v4, v5, v7
	v_mul_f32_e32 v4, v130, v4
	v_bfe_u32 v5, v4, 16, 1
	v_add3_u32 v4, v4, v5, s96
	global_store_short_d16_hi v[2:3], v4, off offset:576
	v_mul_f32_e32 v4, v6, v7
	v_mul_f32_e32 v4, v129, v4
	v_bfe_u32 v5, v4, 16, 1
	v_mul_f32_e32 v0, v0, v7
	v_add3_u32 v4, v4, v5, s96
	v_mul_f32_e32 v0, v128, v0
	global_store_short_d16_hi v[2:3], v4, off offset:640
	v_bfe_u32 v4, v0, 16, 1
	v_add3_u32 v0, v0, v4, s96
	global_store_short_d16_hi v[2:3], v0, off offset:704
	v_rcp_f32_e32 v0, v1
	s_nop 0
	v_mul_f32_e32 v0, s20, v0
	s_waitcnt vmcnt(54)
	v_fma_f32 v3, -v45, v0, v73
	v_fma_f32 v2, -v61, v0, v72
	v_mul_f32_e32 v1, v3, v3
	v_fmac_f32_e32 v1, v2, v2
	v_fma_f32 v4, -v29, v0, v74
	v_fmac_f32_e32 v1, v4, v4
	v_fma_f32 v5, -v13, v0, v75
	v_fmac_f32_e32 v1, v5, v5
	ds_bpermute_b32 v0, v202, v1
	s_waitcnt lgkmcnt(0)
	v_add_f32_e32 v0, v1, v0
	ds_bpermute_b32 v1, v203, v0
	s_waitcnt lgkmcnt(0)
	v_add_f32_e32 v0, v0, v1
	ds_bpermute_b32 v1, v204, v0
	s_waitcnt lgkmcnt(0)
	v_add_f32_e32 v0, v0, v1
	ds_bpermute_b32 v1, v205, v0
	s_waitcnt lgkmcnt(0)
	v_add_f32_e32 v0, v0, v1
	ds_bpermute_b32 v1, v206, v0
	s_waitcnt lgkmcnt(0)
	v_add_f32_e32 v0, v0, v1
	v_fmamk_f32 v0, v0, 0x3c000000, v228
	v_rsq_f32_e32 v6, v0
	v_or_b32_e32 v0, 25, v124
	v_mov_b32_e32 v1, v125
	v_lshlrev_b64 v[0:1], 11, v[0:1]
	v_mul_f32_e32 v2, v2, v6
	v_mul_f32_e32 v2, v131, v2
	v_lshl_add_u64 v[0:1], s[42:43], 0, v[0:1]
	v_bfe_u32 v7, v2, 16, 1
	v_lshl_add_u64 v[0:1], v[0:1], 0, v[152:153]
	v_add3_u32 v2, v2, v7, s96
	global_store_short_d16_hi v[0:1], v2, off offset:512
	v_mul_f32_e32 v2, v3, v6
	v_mul_f32_e32 v2, v130, v2
	v_bfe_u32 v3, v2, 16, 1
	v_add3_u32 v2, v2, v3, s96
	global_store_short_d16_hi v[0:1], v2, off offset:576
	v_mul_f32_e32 v2, v4, v6
	v_mul_f32_e32 v2, v129, v2
	v_bfe_u32 v3, v2, 16, 1
	v_add3_u32 v2, v2, v3, s96
	global_store_short_d16_hi v[0:1], v2, off offset:640
	v_mul_f32_e32 v2, v5, v6
	v_mul_f32_e32 v2, v128, v2
	v_bfe_u32 v3, v2, 16, 1
	v_add3_u32 v2, v2, v3, s96
	global_store_short_d16_hi v[0:1], v2, off offset:704
	ds_read_b64 v[0:1], v240 offset:49256
	s_waitcnt lgkmcnt(0)
	v_rcp_f32_e32 v0, v0
	s_nop 0
	v_mul_f32_e32 v0, s20, v0
	s_waitcnt vmcnt(57)
	v_fma_f32 v5, -v46, v0, v69
	v_fma_f32 v4, -v62, v0, v68
	v_mul_f32_e32 v2, v5, v5
	v_fmac_f32_e32 v2, v4, v4
	v_fma_f32 v6, -v30, v0, v70
	v_fmac_f32_e32 v2, v6, v6
	v_fma_f32 v0, -v14, v0, v71
	v_fmac_f32_e32 v2, v0, v0
	ds_bpermute_b32 v3, v202, v2
	s_waitcnt lgkmcnt(0)
	v_add_f32_e32 v2, v2, v3
	ds_bpermute_b32 v3, v203, v2
	s_waitcnt lgkmcnt(0)
	v_add_f32_e32 v2, v2, v3
	ds_bpermute_b32 v3, v204, v2
	s_waitcnt lgkmcnt(0)
	v_add_f32_e32 v2, v2, v3
	ds_bpermute_b32 v3, v205, v2
	s_waitcnt lgkmcnt(0)
	v_add_f32_e32 v2, v2, v3
	ds_bpermute_b32 v3, v206, v2
	s_waitcnt lgkmcnt(0)
	v_add_f32_e32 v2, v2, v3
	v_fmamk_f32 v2, v2, 0x3c000000, v228
	v_rsq_f32_e32 v7, v2
	v_or_b32_e32 v2, 26, v124
	v_mov_b32_e32 v3, v125
	v_lshlrev_b64 v[2:3], 11, v[2:3]
	v_mul_f32_e32 v4, v4, v7
	v_mul_f32_e32 v4, v131, v4
	v_lshl_add_u64 v[2:3], s[42:43], 0, v[2:3]
	v_bfe_u32 v8, v4, 16, 1
	v_lshl_add_u64 v[2:3], v[2:3], 0, v[152:153]
	v_add3_u32 v4, v4, v8, s96
	global_store_short_d16_hi v[2:3], v4, off offset:512
	v_mul_f32_e32 v4, v5, v7
	v_mul_f32_e32 v4, v130, v4
	v_bfe_u32 v5, v4, 16, 1
	v_add3_u32 v4, v4, v5, s96
	global_store_short_d16_hi v[2:3], v4, off offset:576
	v_mul_f32_e32 v4, v6, v7
	v_mul_f32_e32 v4, v129, v4
	v_bfe_u32 v5, v4, 16, 1
	v_mul_f32_e32 v0, v0, v7
	v_add3_u32 v4, v4, v5, s96
	v_mul_f32_e32 v0, v128, v0
	global_store_short_d16_hi v[2:3], v4, off offset:640
	v_bfe_u32 v4, v0, 16, 1
	v_add3_u32 v0, v0, v4, s96
	global_store_short_d16_hi v[2:3], v0, off offset:704
	v_rcp_f32_e32 v0, v1
	v_or_b32_e32 v124, 27, v124
	v_mul_f32_e32 v0, s20, v0
	s_waitcnt vmcnt(60)
	v_fma_f32 v3, -v47, v0, v65
	v_fma_f32 v2, -v63, v0, v64
	v_mul_f32_e32 v1, v3, v3
	v_fmac_f32_e32 v1, v2, v2
	v_fma_f32 v4, -v31, v0, v66
	v_fmac_f32_e32 v1, v4, v4
	v_fma_f32 v5, -v15, v0, v67
	v_fmac_f32_e32 v1, v5, v5
	ds_bpermute_b32 v0, v202, v1
	s_waitcnt lgkmcnt(0)
	v_add_f32_e32 v0, v1, v0
	ds_bpermute_b32 v1, v203, v0
	s_waitcnt lgkmcnt(0)
	v_add_f32_e32 v0, v0, v1
	ds_bpermute_b32 v1, v204, v0
	s_waitcnt lgkmcnt(0)
	v_add_f32_e32 v0, v0, v1
	ds_bpermute_b32 v1, v205, v0
	s_waitcnt lgkmcnt(0)
	v_add_f32_e32 v0, v0, v1
	ds_bpermute_b32 v1, v206, v0
	s_waitcnt lgkmcnt(0)
	v_add_f32_e32 v0, v0, v1
	v_fmamk_f32 v0, v0, 0x3c000000, v228
	v_rsq_f32_e32 v6, v0
	v_lshlrev_b64 v[0:1], 11, v[124:125]
	v_lshl_add_u64 v[0:1], s[42:43], 0, v[0:1]
	v_lshl_add_u64 v[0:1], v[0:1], 0, v[152:153]
	v_mul_f32_e32 v2, v2, v6
	v_mul_f32_e32 v2, v131, v2
	v_bfe_u32 v7, v2, 16, 1
	v_add3_u32 v2, v2, v7, s96
	global_store_short_d16_hi v[0:1], v2, off offset:512
	v_mul_f32_e32 v2, v3, v6
	v_mul_f32_e32 v2, v130, v2
	v_bfe_u32 v3, v2, 16, 1
	v_add3_u32 v2, v2, v3, s96
	global_store_short_d16_hi v[0:1], v2, off offset:576
	v_mul_f32_e32 v2, v4, v6
	v_mul_f32_e32 v2, v129, v2
	v_bfe_u32 v3, v2, 16, 1
	v_add3_u32 v2, v2, v3, s96
	global_store_short_d16_hi v[0:1], v2, off offset:640
	v_mul_f32_e32 v2, v5, v6
	v_mul_f32_e32 v2, v128, v2
	v_bfe_u32 v3, v2, 16, 1
	v_add3_u32 v2, v2, v3, s96
	global_store_short_d16_hi v[0:1], v2, off offset:704
	s_waitcnt vmcnt(63) expcnt(7) lgkmcnt(15)
	s_barrier
	s_cbranch_vccnz .LBB0_869

.LBB0_833:
	v_lshl_add_u64 v[38:39], s[12:13], 0, v[184:185]
	v_mov_b64_e32 v[40:41], s[94:95]
	v_mad_u64_u32 v[40:41], s[2:3], v38, s60, v[40:41]
	v_mad_i32_i24 v41, v39, s60, v41
	v_mov_b32_e32 v33, v153
	v_lshl_add_u64 v[38:39], v[40:41], 0, v[32:33]
	v_lshl_add_u64 v[40:41], s[12:13], 0, v[186:187]
	v_mov_b64_e32 v[42:43], s[70:71]
	v_mad_u64_u32 v[42:43], s[2:3], v40, s60, v[42:43]
	v_mad_i32_i24 v43, v41, s60, v43
	v_xor_b32_e32 v64, 0x80000000, v36
	v_lshl_add_u64 v[40:41], v[42:43], 0, s[90:91]
	v_mov_b32_e32 v189, v153
	v_mov_b32_e32 v65, v64
	v_mov_b32_e32 v66, v64
	v_mov_b32_e32 v67, v64
	v_mov_b32_e32 v68, v64
	v_mov_b32_e32 v69, v64
	v_mov_b32_e32 v70, v64
	v_mov_b32_e32 v71, v64
	v_mov_b32_e32 v72, v64
	v_mov_b32_e32 v73, v64
	v_mov_b32_e32 v74, v64
	v_mov_b32_e32 v75, v64
	v_mov_b32_e32 v76, v64
	v_mov_b32_e32 v77, v64
	v_mov_b32_e32 v78, v64
	v_mov_b32_e32 v79, v64
	v_lshl_add_u64 v[46:47], v[40:41], 0, v[188:189]
	global_load_dwordx4 v[38:41], v[38:39], off offset:3200
	s_nop 0
	global_load_dwordx4 v[42:45], v[46:47], off
	v_add_co_u32_e32 v46, vcc, s58, v46
	v_sub_f32_e32 v0, v0, v36
	s_nop 0
	v_addc_co_u32_e32 v47, vcc, 0, v47, vcc
	global_load_dwordx4 v[46:49], v[46:47], off
	v_exp_f32_e32 v209, v0
	v_sub_f32_e32 v0, v1, v36
	v_exp_f32_e32 v194, v0
	v_sub_f32_e32 v0, v2, v36
	v_exp_f32_e32 v211, v0
	v_sub_f32_e32 v0, v3, v36
	v_exp_f32_e32 v192, v0
	v_sub_f32_e32 v0, v4, v36
	s_mov_b64 s[2:3], 0x1000
	v_exp_f32_e32 v212, v0
	v_sub_f32_e32 v0, v5, v36
	v_lshl_add_u64 v[146:147], v[144:145], 0, s[2:3]
	s_mov_b64 s[2:3], 0x1400
	v_exp_f32_e32 v198, v0
	v_sub_f32_e32 v0, v6, v36
	v_lshl_add_u64 v[148:149], v[144:145], 0, s[2:3]
	s_mov_b64 s[2:3], 0x1800
	v_exp_f32_e32 v213, v0
	v_sub_f32_e32 v0, v7, v36
	v_lshl_add_u64 v[150:151], v[144:145], 0, s[2:3]
	s_mov_b64 s[2:3], 0x1c00
	v_exp_f32_e32 v196, v0
	v_sub_f32_e32 v0, v8, v36
	v_lshl_add_u64 v[166:167], v[144:145], 0, s[2:3]
	s_mov_b64 s[2:3], 0x2000
	v_exp_f32_e32 v202, v0
	v_sub_f32_e32 v0, v9, v36
	v_lshl_add_u64 v[168:169], v[144:145], 0, s[2:3]
	s_mov_b64 s[2:3], 0x2400
	v_exp_f32_e32 v203, v0
	v_sub_f32_e32 v0, v10, v36
	v_lshl_add_u64 v[170:171], v[144:145], 0, s[2:3]
	s_mov_b64 s[2:3], 0x2800
	v_exp_f32_e32 v200, v0
	v_sub_f32_e32 v0, v11, v36
	v_lshl_add_u64 v[172:173], v[144:145], 0, s[2:3]
	s_mov_b64 s[2:3], 0x2c00
	v_exp_f32_e32 v201, v0
	v_sub_f32_e32 v0, v12, v36
	v_lshl_add_u64 v[174:175], v[144:145], 0, s[2:3]
	s_mov_b64 s[2:3], 0x3000
	v_exp_f32_e32 v206, v0
	v_sub_f32_e32 v0, v13, v36
	v_lshl_add_u64 v[176:177], v[144:145], 0, s[2:3]
	s_mov_b64 s[2:3], 0x3400
	v_and_b32_e32 v245, 63, v34
	v_exp_f32_e32 v207, v0
	v_sub_f32_e32 v0, v14, v36
	v_lshl_add_u64 v[178:179], v[144:145], 0, s[2:3]
	s_mov_b64 s[2:3], 0x3800
	v_lshlrev_b32_e32 v37, 3, v245
	v_and_b32_e32 v35, 0xc0, v35
	v_lshlrev_b32_e32 v34, 1, v34
	v_exp_f32_e32 v204, v0
	v_sub_f32_e32 v0, v15, v36
	v_lshl_add_u64 v[180:181], v[144:145], 0, s[2:3]
	s_mov_b64 s[2:3], 0x3c00
	v_and_or_b32 v35, v37, 24, v35
	v_and_b32_e32 v34, 32, v34
	v_and_b32_e32 v37, 0x100, v37
	s_cmp_lg_u32 0, -1
	v_exp_f32_e32 v205, v0
	v_lshl_add_u64 v[182:183], v[144:145], 0, s[2:3]
	v_or3_b32 v34, v35, v34, v37
	s_cselect_b32 s2, 0, 0
	v_add_u32_e32 v248, s2, v34
	s_addk_i32 s2, 0x4000
	v_mov_b32_e32 v246, 0
	v_sub_f32_e32 v95, v31, v36
	v_sub_f32_e32 v94, v30, v36
	v_sub_f32_e32 v93, v29, v36
	v_sub_f32_e32 v92, v28, v36
	v_sub_f32_e32 v91, v27, v36
	v_sub_f32_e32 v90, v26, v36
	v_sub_f32_e32 v89, v25, v36
	v_sub_f32_e32 v88, v24, v36
	v_sub_f32_e32 v87, v23, v36
	v_sub_f32_e32 v86, v22, v36
	v_sub_f32_e32 v85, v21, v36
	v_sub_f32_e32 v84, v20, v36
	v_sub_f32_e32 v83, v19, v36
	v_sub_f32_e32 v82, v18, v36
	v_sub_f32_e32 v81, v17, v36
	v_sub_f32_e32 v80, v16, v36
	s_waitcnt vmcnt(2)
	ds_write_b128 v251, v[38:41] offset:40960
	s_waitcnt vmcnt(1)
	ds_write_b128 v252, v[42:45] offset:16384
	s_waitcnt vmcnt(0)
	ds_write_b128 v231, v[46:49] offset:16384
	v_add_u32_e32 v247, s2, v34
	v_lshl_add_u64 v[190:191], s[94:95], 0, v[32:33]
	s_mov_b64 s[16:17], 0
	s_movk_i32 s19, 0x80
	s_mov_b32 s21, 2
	s_add_i32 s48, s10, 0x80
	v_lshl_add_u64 v[178:179], s[48:49], 0, v[184:185]
	v_mad_u64_u32 v[180:181], s[100:101], v178, s60, v[190:191]
	v_mad_i32_i24 v181, v179, s60, v181
	v_lshl_add_u64 v[178:179], s[48:49], 0, v[186:187]
	v_mov_b64_e32 v[182:183], s[70:71]
	global_load_dwordx4 v[166:169], v[180:181], off offset:3200
	v_mad_u64_u32 v[180:181], s[100:101], v178, s60, v[182:183]
	v_mad_i32_i24 v181, v179, s60, v181
	s_mov_b32 s91, s49
	v_lshl_add_u64 v[178:179], v[180:181], 0, s[90:91]
	v_lshl_add_u64 v[178:179], v[178:179], 0, v[188:189]
	s_mov_b32 s100, s58
	s_mov_b32 s101, 0
	v_lshl_add_u64 v[180:181], v[178:179], 0, s[100:101]
	global_load_dwordx4 v[170:173], v[178:179], off
	global_load_dwordx4 v[174:177], v[180:181], off
	v_mov_b32_e32 v0, 0
	v_mov_b32_e32 v1, v246
	v_mov_b32_e32 v2, v246
	v_mov_b32_e32 v3, v246
	v_mov_b32_e32 v4, v246
	v_mov_b32_e32 v5, v246
	v_mov_b32_e32 v6, v246
	v_mov_b32_e32 v7, v246
	v_mov_b32_e32 v8, v246
	v_mov_b32_e32 v9, v246
	v_mov_b32_e32 v10, v246
	v_mov_b32_e32 v11, v246
	v_mov_b32_e32 v12, v246
	v_mov_b32_e32 v13, v246
	v_mov_b32_e32 v14, v246
	v_mov_b32_e32 v15, v246
	v_mov_b32_e32 v16, 0
	v_mov_b32_e32 v17, v246
	v_mov_b32_e32 v18, v246
	v_mov_b32_e32 v19, v246
	v_mov_b32_e32 v20, v246
	v_mov_b32_e32 v21, v246
	v_mov_b32_e32 v22, v246
	v_mov_b32_e32 v23, v246
	v_mov_b32_e32 v24, v246
	v_mov_b32_e32 v25, v246
	v_mov_b32_e32 v26, v246
	v_mov_b32_e32 v27, v246
	v_mov_b32_e32 v28, v246
	v_mov_b32_e32 v29, v246
	v_mov_b32_e32 v30, v246
	v_mov_b32_e32 v31, v246
	v_mov_b32_e32 v32, 0
	v_mov_b32_e32 v33, v246
	v_mov_b32_e32 v34, v246
	v_mov_b32_e32 v35, v246
	v_mov_b32_e32 v36, v246
	v_mov_b32_e32 v37, v246
	v_mov_b32_e32 v38, v246
	v_mov_b32_e32 v39, v246
	v_mov_b32_e32 v40, v246
	v_mov_b32_e32 v41, v246
	v_mov_b32_e32 v42, v246
	v_mov_b32_e32 v43, v246
	v_mov_b32_e32 v44, v246
	v_mov_b32_e32 v45, v246
	v_mov_b32_e32 v46, v246
	v_mov_b32_e32 v47, v246
	v_mov_b32_e32 v48, 0
	v_mov_b32_e32 v49, v246
	v_mov_b32_e32 v50, v246
	v_mov_b32_e32 v51, v246
	v_mov_b32_e32 v52, v246
	v_mov_b32_e32 v53, v246
	v_mov_b32_e32 v54, v246
	v_mov_b32_e32 v55, v246
	v_mov_b32_e32 v56, v246
	v_mov_b32_e32 v57, v246
	v_mov_b32_e32 v58, v246
	v_mov_b32_e32 v59, v246
	v_mov_b32_e32 v60, v246
	v_mov_b32_e32 v61, v246
	v_mov_b32_e32 v62, v246
	v_mov_b32_e32 v63, v246
	s_waitcnt lgkmcnt(0)
	s_barrier
	v_xor_b32_e32 v251, 0x10000, v251
	v_xor_b32_e32 v252, 0x10000, v252
	v_xor_b32_e32 v231, 0x10000, v231
.LBB0_834:
	ds_read_b128 v[214:217], v249 offset:45056
	ds_read_b128 v[112:115], v249 offset:40960
	v_exp_f32_e32 v152, v80
	v_exp_f32_e32 v193, v81
	v_exp_f32_e32 v195, v82
	v_exp_f32_e32 v197, v83
	s_waitcnt lgkmcnt(0)
	v_mfma_f32_32x32x16_bf16 v[96:111], v[112:115], v[140:143], v[64:79]
	v_exp_f32_e32 v199, v84
	v_add_f32_e32 v80, v209, v152
	v_add_f32_e32 v80, 0, v80
	v_add_f32_e32 v81, v194, v193
	v_add_f32_e32 v80, v81, v80
	v_add_f32_e32 v81, v211, v195
	v_add_f32_e32 v80, v81, v80
	v_mfma_f32_32x32x16_bf16 v[112:127], v[214:217], v[140:143], v[64:79]
	ds_read_b128 v[214:217], v250 offset:45056
	ds_read_b128 v[218:221], v250 offset:40960
	v_add_f32_e32 v81, v192, v197
	v_exp_f32_e32 v154, v88
	v_exp_f32_e32 v155, v89
	v_add_f32_e32 v80, v81, v80
	v_add_f32_e32 v81, v212, v199
	v_add_f32_e32 v80, v81, v80
	s_waitcnt lgkmcnt(1)
	v_mfma_f32_32x32x16_bf16 v[112:127], v[214:217], v[136:139], v[112:127]
	v_exp_f32_e32 v156, v90
	v_exp_f32_e32 v157, v91
	v_exp_f32_e32 v158, v92
	v_exp_f32_e32 v159, v93
	v_exp_f32_e32 v160, v94
	v_exp_f32_e32 v161, v95
	s_waitcnt lgkmcnt(0)
	v_mfma_f32_32x32x16_bf16 v[96:111], v[218:221], v[136:139], v[96:111]
	ds_read_b128 v[214:217], v233 offset:45056
	ds_read_b128 v[218:221], v233 offset:40960
	s_waitcnt lgkmcnt(1)
	v_mfma_f32_32x32x16_bf16 v[112:127], v[214:217], v[132:135], v[112:127]
	s_waitcnt lgkmcnt(0)
	v_mfma_f32_32x32x16_bf16 v[96:111], v[218:221], v[132:135], v[96:111]
	ds_read_b128 v[214:217], v232 offset:45056
	ds_read_b128 v[218:221], v232 offset:40960
	s_waitcnt lgkmcnt(1)
	v_mfma_f32_32x32x16_bf16 v[112:127], v[214:217], v[128:131], v[112:127]
	v_exp_f32_e32 v214, v85
	v_exp_f32_e32 v215, v86
	v_exp_f32_e32 v216, v87
	v_add_f32_e32 v81, v198, v214
	v_add_f32_e32 v80, v81, v80
	v_add_f32_e32 v81, v213, v215
	v_add_f32_e32 v80, v81, v80
	v_add_f32_e32 v81, v196, v216
	v_add_f32_e32 v82, v81, v80
	v_pk_add_f32 v[80:81], v[202:203], v[154:155]
	s_waitcnt lgkmcnt(0)
	v_mfma_f32_32x32x16_bf16 v[96:111], v[218:221], v[128:131], v[96:111]
	v_add_f32_e32 v80, v80, v82
	v_add_f32_e32 v82, v81, v80
	v_add_f32_e64 v80, v200, v156
	v_add_f32_e64 v81, v201, v157
	v_add_f32_e32 v80, v80, v82
	v_add_f32_e32 v82, v81, v80
	v_pk_add_f32 v[80:81], v[206:207], v[158:159]
	s_nop 0
	v_add_f32_e32 v80, v80, v82
	v_add_f32_e32 v82, v81, v80
	v_pk_add_f32 v[80:81], v[204:205], v[160:161]
	s_nop 0
	v_add_f32_e32 v80, v80, v82
	v_add_f32_e32 v208, v81, v80
	v_cvt_pk_bf16_f32 v80, v209, v194
	v_cvt_pk_bf16_f32 v81, v211, v192
	v_cvt_pk_bf16_f32 v82, v212, v198
	v_cvt_pk_bf16_f32 v83, v213, v196
	v_cvt_pk_bf16_f32 v84, v202, v203
	v_cvt_pk_bf16_f32 v85, v200, v201
	v_cvt_pk_bf16_f32 v86, v206, v207
	v_cvt_pk_bf16_f32 v87, v204, v205
	v_cvt_pk_bf16_f32 v88, v152, v193
	v_cvt_pk_bf16_f32 v89, v195, v197
	v_cvt_pk_bf16_f32 v90, v199, v214
	v_cvt_pk_bf16_f32 v91, v215, v216
	v_cvt_pk_bf16_f32 v92, v154, v155
	v_cvt_pk_bf16_f32 v93, v156, v157
	v_cvt_pk_bf16_f32 v94, v158, v159
	v_cvt_pk_bf16_f32 v95, v160, v161
	v_mov_b32_e32 v210, v208
	v_permlane32_swap_b32_e32 v80, v82
	v_permlane32_swap_b32_e32 v81, v83
	v_permlane32_swap_b32_e32 v84, v86
	v_permlane32_swap_b32_e32 v85, v87
	v_permlane32_swap_b32_e32 v88, v90
	v_permlane32_swap_b32_e32 v89, v91
	v_permlane32_swap_b32_e32 v92, v94
	v_permlane32_swap_b32_e32 v93, v95
	v_permlane32_swap_b32_e32 v208, v210
	s_add_i32 s2, s19, 64
	s_and_b32 s2, s2, 0x7c0
	s_cmp_lt_u32 s21, 31
	s_cselect_b32 s3, s10, s18
	s_add_i32 s48, s3, s2
	v_lshl_add_u64 v[154:155], s[48:49], 0, v[184:185]
	v_mad_u64_u32 v[156:157], s[2:3], v154, s60, v[190:191]
	v_mad_i32_i24 v157, v155, s60, v157
	v_lshl_add_u64 v[154:155], s[48:49], 0, v[186:187]
	v_mov_b64_e32 v[192:193], s[70:71]
	global_load_dwordx4 v[178:181], v[156:157], off offset:3200
	v_mad_u64_u32 v[156:157], s[2:3], v154, s60, v[192:193]
	v_mad_i32_i24 v157, v155, s60, v157
	s_mov_b32 s91, s49
	v_lshl_add_u64 v[154:155], v[156:157], 0, s[90:91]
	v_lshl_add_u64 v[154:155], v[154:155], 0, v[188:189]
	v_add_co_u32_e32 v156, vcc, s58, v154
	s_nop 1
	v_addc_co_u32_e32 v157, vcc, 0, v155, vcc
	global_load_dwordx4 v[148:151], v[154:155], off
	s_nop 0
	global_load_dwordx2 v[146:147], v[156:157], off
	global_load_dwordx2 v[182:183], v[156:157], off offset:8
	ds_read_b64_tr_b16 v[194:195], v248 offset:0
	ds_read_b64_tr_b16 v[196:197], v248 offset:0x800
	ds_read_b64_tr_b16 v[198:199], v248 offset:0x1000
	ds_read_b64_tr_b16 v[200:201], v248 offset:0x1800
	ds_read_b64_tr_b16 v[202:203], v248 offset:0x2000
	ds_read_b64_tr_b16 v[204:205], v248 offset:0x2800
	ds_read_b64_tr_b16 v[216:217], v248 offset:0x3000
	ds_read_b64_tr_b16 v[218:219], v248 offset:0x3800
	s_waitcnt lgkmcnt(0)
	s_nop 0
	v_mfma_f32_32x32x16_bf16 v[48:63], v[80:83], v[194:197], v[48:63]
	v_exp_f32_e32 v238, v96
	v_exp_f32_e32 v194, v97
	ds_read_b64_tr_b16 v[96:97], v248 offset:0x200
	v_exp_f32_e32 v236, v98
	v_exp_f32_e32 v196, v99
	ds_read_b64_tr_b16 v[98:99], v248 offset:0xa00
	v_mfma_f32_32x32x16_bf16 v[48:63], v[84:87], v[198:201], v[48:63]
	ds_read_b64_tr_b16 v[198:199], v248 offset:0x1200
	ds_read_b64_tr_b16 v[200:201], v248 offset:0x1a00
	v_mfma_f32_32x32x16_bf16 v[48:63], v[88:91], v[202:205], v[48:63]
	ds_read_b64_tr_b16 v[202:203], v248 offset:0x2200
	ds_read_b64_tr_b16 v[204:205], v248 offset:0x2a00
	v_mfma_f32_32x32x16_bf16 v[48:63], v[92:95], v[216:219], v[48:63]
	ds_read_b64_tr_b16 v[216:217], v248 offset:0x3200
	ds_read_b64_tr_b16 v[218:219], v248 offset:0x3a00
	s_waitcnt lgkmcnt(0)
	v_mfma_f32_32x32x16_bf16 v[32:47], v[80:83], v[96:99], v[32:47]
	s_waitcnt vmcnt(4)
	ds_write_b128 v251, v[166:169] offset:32768
	ds_write_b128 v252, v[170:173]
	ds_write_b128 v231, v[174:177]
	ds_read_b64_tr_b16 v[96:97], v248 offset:0x400
	ds_read_b64_tr_b16 v[98:99], v248 offset:0xc00
	v_exp_f32_e32 v237, v100
	v_exp_f32_e32 v162, v102
	v_mfma_f32_32x32x16_bf16 v[32:47], v[84:87], v[198:201], v[32:47]
	v_exp_f32_e32 v198, v101
	ds_read_b64_tr_b16 v[100:101], v248 offset:0x1400
	v_exp_f32_e32 v200, v103
	ds_read_b64_tr_b16 v[102:103], v248 offset:0x1c00
	v_mfma_f32_32x32x16_bf16 v[32:47], v[88:91], v[202:205], v[32:47]
	ds_read_b64_tr_b16 v[202:203], v248 offset:0x2400
	ds_read_b64_tr_b16 v[204:205], v248 offset:0x2c00
	v_mfma_f32_32x32x16_bf16 v[32:47], v[92:95], v[216:219], v[32:47]
	ds_read_b64_tr_b16 v[216:217], v248 offset:0x3400
	ds_read_b64_tr_b16 v[218:219], v248 offset:0x3c00
	v_xor_b32_e32 v249, 0x10000, v249
	v_xor_b32_e32 v250, 0x10000, v250
	v_xor_b32_e32 v233, 0x10000, v233
	v_xor_b32_e32 v232, 0x10000, v232
	s_waitcnt lgkmcnt(0)
	v_mfma_f32_32x32x16_bf16 v[16:31], v[80:83], v[96:99], v[16:31]
	ds_read_b64_tr_b16 v[96:97], v248 offset:0x600
	ds_read_b64_tr_b16 v[98:99], v248 offset:0xe00
	v_exp_f32_e32 v163, v104
	v_exp_f32_e32 v164, v106
	v_mfma_f32_32x32x16_bf16 v[16:31], v[84:87], v[100:103], v[16:31]
	ds_read_b64_tr_b16 v[100:101], v248 offset:0x1600
	ds_read_b64_tr_b16 v[102:103], v248 offset:0x1e00
	v_mfma_f32_32x32x16_bf16 v[16:31], v[88:91], v[202:205], v[16:31]
	v_exp_f32_e32 v202, v105
	ds_read_b64_tr_b16 v[104:105], v248 offset:0x2600
	v_exp_f32_e32 v204, v107
	ds_read_b64_tr_b16 v[106:107], v248 offset:0x2e00
	ds_read_b64_tr_b16 v[158:159], v248 offset:0x3600
	ds_read_b64_tr_b16 v[160:161], v248 offset:0x3e00
	s_waitcnt lgkmcnt(0)
	v_mfma_f32_32x32x16_bf16 v[16:31], v[92:95], v[216:219], v[16:31]
	v_mfma_f32_32x32x16_bf16 v[0:15], v[80:83], v[96:99], v[0:15]
	v_exp_f32_e32 v165, v108
	v_exp_f32_e32 v218, v109
	v_exp_f32_e32 v235, v110
	v_exp_f32_e32 v220, v111
	v_mfma_f32_32x32x16_bf16 v[0:15], v[84:87], v[100:103], v[0:15]
	s_waitcnt lgkmcnt(0)
	s_barrier
	v_mfma_f32_32x32x16_bf16 v[0:15], v[88:91], v[104:107], v[0:15]
	v_mfma_f32_32x32x16_bf16 v[0:15], v[92:95], v[158:161], v[0:15]
	ds_read_b128 v[154:157], v249 offset:36864
	ds_read_b128 v[80:83], v249 offset:32768
	v_exp_f32_e32 v152, v113
	v_exp_f32_e32 v222, v115
	v_exp_f32_e32 v224, v117
	v_exp_f32_e32 v226, v119
	s_waitcnt lgkmcnt(0)
	v_mfma_f32_32x32x16_bf16 v[96:111], v[80:83], v[140:143], v[64:79]
	v_exp_f32_e32 v206, v121
	v_exp_f32_e32 v212, v123
	v_exp_f32_e32 v214, v125
	v_exp_f32_e32 v216, v127
	v_mfma_f32_32x32x16_bf16 v[80:95], v[154:157], v[140:143], v[64:79]
	ds_read_b128 v[154:157], v250 offset:36864
	ds_read_b128 v[158:161], v250 offset:32768
	s_waitcnt lgkmcnt(1)
	v_mfma_f32_32x32x16_bf16 v[80:95], v[154:157], v[136:139], v[80:95]
	s_waitcnt lgkmcnt(0)
	v_mfma_f32_32x32x16_bf16 v[96:111], v[158:161], v[136:139], v[96:111]
	ds_read_b128 v[154:157], v233 offset:36864
	ds_read_b128 v[158:161], v233 offset:32768
	s_waitcnt lgkmcnt(1)
	v_mfma_f32_32x32x16_bf16 v[80:95], v[154:157], v[132:135], v[80:95]
	s_waitcnt lgkmcnt(0)
	v_mfma_f32_32x32x16_bf16 v[96:111], v[158:161], v[132:135], v[96:111]
	ds_read_b128 v[154:157], v232 offset:36864
	ds_read_b128 v[158:161], v232 offset:32768
	s_waitcnt lgkmcnt(1)
	v_mfma_f32_32x32x16_bf16 v[80:95], v[154:157], v[128:131], v[80:95]
	v_exp_f32_e32 v154, v112
	v_exp_f32_e32 v155, v114
	v_exp_f32_e32 v156, v116
	v_exp_f32_e32 v157, v118
	v_add_f32_e32 v195, v238, v154
	v_pk_add_f32 v[112:113], v[194:195], v[152:153]
	v_add_f32_e32 v197, v236, v155
	v_pk_add_f32 v[112:113], v[112:113], v[112:113] op_sel_hi:[0,1]
	v_mov_b32_e32 v223, v113
	v_pk_add_f32 v[112:113], v[196:197], v[222:223]
	v_add_f32_e32 v199, v237, v156
	v_pk_add_f32 v[112:113], v[112:113], v[112:113] op_sel_hi:[0,1]
	v_mov_b32_e32 v225, v113
	v_pk_add_f32 v[112:113], v[198:199], v[224:225]
	s_waitcnt lgkmcnt(0)
	v_mfma_f32_32x32x16_bf16 v[96:111], v[158:161], v[128:131], v[96:111]
	v_exp_f32_e32 v158, v120
	v_pk_add_f32 v[112:113], v[112:113], v[112:113] op_sel_hi:[0,1]
	v_add_f32_e32 v201, v162, v157
	v_mov_b32_e32 v227, v113
	v_pk_add_f32 v[112:113], v[200:201], v[226:227]
	v_exp_f32_e32 v159, v122
	v_pk_add_f32 v[112:113], v[112:113], v[112:113] op_sel_hi:[0,1]
	v_add_f32_e32 v203, v163, v158
	v_mov_b32_e32 v207, v113
	v_pk_add_f32 v[112:113], v[202:203], v[206:207]
	v_exp_f32_e32 v160, v124
	v_pk_add_f32 v[112:113], v[112:113], v[112:113] op_sel_hi:[0,1]
	v_add_f32_e32 v205, v164, v159
	v_mov_b32_e32 v213, v113
	v_pk_add_f32 v[112:113], v[204:205], v[212:213]
	v_exp_f32_e32 v161, v126
	v_pk_add_f32 v[112:113], v[112:113], v[112:113] op_sel_hi:[0,1]
	v_add_f32_e32 v219, v165, v160
	v_mov_b32_e32 v215, v113
	v_pk_add_f32 v[112:113], v[218:219], v[214:215]
	v_add_f32_e32 v221, v235, v161
	v_pk_add_f32 v[112:113], v[112:113], v[112:113] op_sel_hi:[0,1]
	v_mov_b32_e32 v217, v113
	v_pk_add_f32 v[112:113], v[220:221], v[216:217]
	s_nop 0
	v_pk_add_f32 v[112:113], v[112:113], v[112:113] op_sel:[0,1] op_sel_hi:[1,0]
	s_nop 0
	v_mov_b32_e32 v211, v112
	s_nop 1
	v_permlane32_swap_b32_e32 v112, v211
	v_mov_b32_e32 v209, v112
	v_pk_add_f32 v[112:113], v[208:209], v[210:211]
	s_nop 0
	v_cmp_ngt_f32_e32 vcc, s59, v113
	v_cmp_ngt_f32_e64 s[2:3], s59, v112
	v_fma_f32 v114, v246, v234, v112
	s_or_b64 s[2:3], s[2:3], vcc
	v_add_f32_e32 v246, v114, v113
	s_or_b64 s[16:17], s[16:17], s[2:3]
	v_cvt_pk_bf16_f32 v112, v238, v194
	v_cvt_pk_bf16_f32 v113, v236, v196
	v_cvt_pk_bf16_f32 v114, v237, v198
	v_cvt_pk_bf16_f32 v115, v162, v200
	v_cvt_pk_bf16_f32 v116, v163, v202
	v_cvt_pk_bf16_f32 v117, v164, v204
	v_cvt_pk_bf16_f32 v118, v165, v218
	v_cvt_pk_bf16_f32 v119, v235, v220
	v_cvt_pk_bf16_f32 v120, v154, v152
	v_cvt_pk_bf16_f32 v121, v155, v222
	v_cvt_pk_bf16_f32 v122, v156, v224
	v_cvt_pk_bf16_f32 v123, v157, v226
	v_cvt_pk_bf16_f32 v124, v158, v206
	v_cvt_pk_bf16_f32 v125, v159, v212
	v_cvt_pk_bf16_f32 v126, v160, v214
	v_cvt_pk_bf16_f32 v127, v161, v216
	s_nop 0
	v_permlane32_swap_b32_e32 v112, v114
	v_permlane32_swap_b32_e32 v113, v115
	v_permlane32_swap_b32_e32 v116, v118
	v_permlane32_swap_b32_e32 v117, v119
	v_permlane32_swap_b32_e32 v120, v122
	v_permlane32_swap_b32_e32 v121, v123
	v_permlane32_swap_b32_e32 v124, v126
	v_permlane32_swap_b32_e32 v125, v127
	s_add_i32 s2, s21, -1
	s_cmp_lt_u32 s21, 30
	s_cselect_b32 s3, 0, 0xffffffe0
	s_cselect_b32 s22, s10, s18
	s_add_i32 s3, s3, s21
	s_lshl_b32 s3, s3, 6
	s_add_i32 s3, s3, s22
	s_add_i32 s48, s3, 0x80
	v_lshl_add_u64 v[158:159], s[48:49], 0, v[186:187]
	v_mad_u64_u32 v[160:161], s[22:23], v158, s60, v[192:193]
	v_mad_i32_i24 v161, v159, s60, v161
	v_lshl_add_u64 v[154:155], s[48:49], 0, v[184:185]
	v_lshl_add_u64 v[158:159], v[160:161], 0, s[90:91]
	v_mad_u64_u32 v[156:157], s[22:23], v154, s60, v[190:191]
	v_lshl_add_u64 v[158:159], v[158:159], 0, v[188:189]
	v_mad_i32_i24 v157, v155, s60, v157
	v_add_co_u32_e32 v192, vcc, s58, v158
	global_load_dwordx4 v[166:169], v[156:157], off offset:3200
	s_nop 0
	v_addc_co_u32_e32 v193, vcc, 0, v159, vcc
	global_load_dwordx4 v[170:173], v[158:159], off
	s_nop 0
	global_load_dwordx4 v[174:177], v[192:193], off
	ds_read_b64_tr_b16 v[192:193], v247 offset:0
	ds_read_b64_tr_b16 v[194:195], v247 offset:0x800
	ds_read_b64_tr_b16 v[196:197], v247 offset:0x1000
	ds_read_b64_tr_b16 v[198:199], v247 offset:0x1800
	ds_read_b64_tr_b16 v[200:201], v247 offset:0x2000
	ds_read_b64_tr_b16 v[202:203], v247 offset:0x2800
	ds_read_b64_tr_b16 v[204:205], v247 offset:0x3000
	ds_read_b64_tr_b16 v[206:207], v247 offset:0x3800
	s_waitcnt lgkmcnt(0)
	s_nop 0
	v_mfma_f32_32x32x16_bf16 v[48:63], v[112:115], v[192:195], v[48:63]
	v_exp_f32_e32 v209, v96
	v_exp_f32_e32 v194, v97
	ds_read_b64_tr_b16 v[96:97], v247 offset:0x200
	v_exp_f32_e32 v211, v98
	v_exp_f32_e32 v192, v99
	ds_read_b64_tr_b16 v[98:99], v247 offset:0xa00
	v_mfma_f32_32x32x16_bf16 v[48:63], v[116:119], v[196:199], v[48:63]
	ds_read_b64_tr_b16 v[196:197], v247 offset:0x1200
	ds_read_b64_tr_b16 v[198:199], v247 offset:0x1a00
	v_mfma_f32_32x32x16_bf16 v[48:63], v[120:123], v[200:203], v[48:63]
	ds_read_b64_tr_b16 v[200:201], v247 offset:0x2200
	ds_read_b64_tr_b16 v[202:203], v247 offset:0x2a00
	v_mfma_f32_32x32x16_bf16 v[48:63], v[124:127], v[204:207], v[48:63]
	ds_read_b64_tr_b16 v[204:205], v247 offset:0x3200
	ds_read_b64_tr_b16 v[206:207], v247 offset:0x3a00
	s_waitcnt lgkmcnt(0)
	v_mfma_f32_32x32x16_bf16 v[32:47], v[112:115], v[96:99], v[32:47]
	s_waitcnt vmcnt(3)
	ds_write_b128 v251, v[178:181] offset:40960
	ds_write_b128 v252, v[148:151] offset:16384
	ds_write_b64 v231, v[146:147] offset:16384
	ds_write_b64 v231, v[182:183] offset:16392
	ds_read_b64_tr_b16 v[96:97], v247 offset:0x400
	ds_read_b64_tr_b16 v[98:99], v247 offset:0xc00
	v_exp_f32_e32 v212, v100
	v_exp_f32_e32 v213, v102
	v_mfma_f32_32x32x16_bf16 v[32:47], v[116:119], v[196:199], v[32:47]
	v_exp_f32_e32 v198, v101
	ds_read_b64_tr_b16 v[100:101], v247 offset:0x1400
	v_exp_f32_e32 v196, v103
	ds_read_b64_tr_b16 v[102:103], v247 offset:0x1c00
	v_mfma_f32_32x32x16_bf16 v[32:47], v[120:123], v[200:203], v[32:47]
	ds_read_b64_tr_b16 v[200:201], v247 offset:0x2400
	ds_read_b64_tr_b16 v[202:203], v247 offset:0x2c00
	v_mfma_f32_32x32x16_bf16 v[32:47], v[124:127], v[204:207], v[32:47]
	ds_read_b64_tr_b16 v[204:205], v247 offset:0x3400
	ds_read_b64_tr_b16 v[206:207], v247 offset:0x3c00
	v_xor_b32_e32 v248, 0x10000, v248
	s_waitcnt lgkmcnt(0)
	v_mfma_f32_32x32x16_bf16 v[16:31], v[112:115], v[96:99], v[16:31]
	ds_read_b64_tr_b16 v[96:97], v247 offset:0x600
	ds_read_b64_tr_b16 v[98:99], v247 offset:0xe00
	v_mfma_f32_32x32x16_bf16 v[16:31], v[116:119], v[100:103], v[16:31]
	ds_read_b64_tr_b16 v[100:101], v247 offset:0x1600
	ds_read_b64_tr_b16 v[102:103], v247 offset:0x1e00
	v_mfma_f32_32x32x16_bf16 v[16:31], v[120:123], v[200:203], v[16:31]
	v_exp_f32_e32 v202, v104
	v_exp_f32_e32 v203, v105
	ds_read_b64_tr_b16 v[104:105], v247 offset:0x2600
	v_exp_f32_e32 v200, v106
	v_exp_f32_e32 v201, v107
	ds_read_b64_tr_b16 v[106:107], v247 offset:0x2e00
	ds_read_b64_tr_b16 v[218:219], v247 offset:0x3600
	v_mfma_f32_32x32x16_bf16 v[16:31], v[124:127], v[204:207], v[16:31]
	ds_read_b64_tr_b16 v[220:221], v247 offset:0x3e00
	s_waitcnt lgkmcnt(0)
	v_mfma_f32_32x32x16_bf16 v[0:15], v[112:115], v[96:99], v[0:15]
	v_exp_f32_e32 v206, v108
	v_exp_f32_e32 v207, v109
	v_exp_f32_e32 v204, v110
	v_exp_f32_e32 v205, v111
	s_andn2_b64 s[14:15], s[14:15], exec
	s_and_b64 s[22:23], s[16:17], exec
	s_addk_i32 s19, 0x80
	v_mfma_f32_32x32x16_bf16 v[0:15], v[116:119], v[100:103], v[0:15]
	s_add_i32 s21, s21, 2
	s_or_b64 s[14:15], s[14:15], s[22:23]
	s_cmp_gt_u32 s2, 32
	v_mov_b32_e32 v234, 1.0
	v_mfma_f32_32x32x16_bf16 v[0:15], v[120:123], v[104:107], v[0:15]
	v_xor_b32_e32 v247, 0x10000, v247
	v_xor_b32_e32 v251, 0x10000, v251
	v_xor_b32_e32 v252, 0x10000, v252
	v_xor_b32_e32 v231, 0x10000, v231
	s_waitcnt lgkmcnt(0)
	s_barrier
	v_mfma_f32_32x32x16_bf16 v[0:15], v[124:127], v[218:221], v[0:15]
	s_cbranch_scc0 .LBB0_834
	ds_read_b128 v[112:115], v249 offset:45056
	ds_read_b128 v[116:119], v249 offset:40960
	v_exp_f32_e32 v152, v81
	v_exp_f32_e32 v124, v84
	v_exp_f32_e32 v84, v85
	v_exp_f32_e32 v125, v86
	s_waitcnt lgkmcnt(0)
	v_mfma_f32_32x32x16_bf16 v[96:111], v[116:119], v[140:143], v[64:79]
	v_exp_f32_e32 v86, v87
	v_add_f32_e32 v199, v212, v124
	v_exp_f32_e32 v126, v88
	v_add_f32_e32 v197, v213, v125
	v_exp_f32_e32 v127, v90
	v_exp_f32_e32 v120, v93
	v_exp_f32_e32 v122, v95
	v_mfma_f32_32x32x16_bf16 v[64:79], v[112:115], v[140:143], v[64:79]
	ds_read_b128 v[112:115], v250 offset:45056
	ds_read_b128 v[116:119], v250 offset:40960
	s_waitcnt lgkmcnt(1)
	v_mfma_f32_32x32x16_bf16 v[64:79], v[112:115], v[136:139], v[64:79]
	s_waitcnt lgkmcnt(0)
	v_mfma_f32_32x32x16_bf16 v[96:111], v[116:119], v[136:139], v[96:111]
	ds_read_b128 v[112:115], v233 offset:45056
	ds_read_b128 v[116:119], v233 offset:40960
	s_waitcnt lgkmcnt(1)
	v_mfma_f32_32x32x16_bf16 v[64:79], v[112:115], v[132:135], v[64:79]
	s_waitcnt lgkmcnt(0)
	v_mfma_f32_32x32x16_bf16 v[96:111], v[116:119], v[132:135], v[96:111]
	ds_read_b128 v[112:115], v232 offset:45056
	ds_read_b128 v[116:119], v232 offset:40960
	v_cvt_pk_bf16_f32 v88, v209, v194
	s_waitcnt lgkmcnt(1)
	v_mfma_f32_32x32x16_bf16 v[64:79], v[112:115], v[128:131], v[64:79]
	v_exp_f32_e32 v112, v80
	v_exp_f32_e32 v113, v82
	v_exp_f32_e32 v114, v83
	v_add_f32_e32 v83, v202, v126
	v_add_f32_e32 v195, v209, v112
	v_pk_add_f32 v[80:81], v[194:195], v[152:153]
	v_add_f32_e32 v193, v211, v113
	v_pk_add_f32 v[80:81], v[80:81], v[80:81] op_sel_hi:[0,1]
	v_mov_b32_e32 v115, v81
	v_pk_add_f32 v[80:81], v[192:193], v[114:115]
	s_waitcnt lgkmcnt(0)
	v_mfma_f32_32x32x16_bf16 v[96:111], v[116:119], v[128:131], v[96:111]
	v_pk_add_f32 v[80:81], v[80:81], v[80:81] op_sel_hi:[0,1]
	v_mov_b32_e32 v85, v81
	v_pk_add_f32 v[80:81], v[198:199], v[84:85]
	v_exp_f32_e32 v116, v89
	v_pk_add_f32 v[80:81], v[80:81], v[80:81] op_sel_hi:[0,1]
	v_mov_b32_e32 v87, v81
	v_pk_add_f32 v[80:81], v[196:197], v[86:87]
	v_exp_f32_e32 v118, v91
	v_pk_add_f32 v[80:81], v[80:81], v[80:81] op_sel_hi:[0,1]
	v_mov_b32_e32 v82, v203
	v_mov_b32_e32 v117, v81
	v_pk_add_f32 v[80:81], v[82:83], v[116:117]
	v_exp_f32_e32 v128, v92
	v_pk_add_f32 v[80:81], v[80:81], v[80:81] op_sel_hi:[0,1]
	v_add_f32_e32 v83, v200, v127
	v_mov_b32_e32 v82, v201
	v_mov_b32_e32 v119, v81
	v_pk_add_f32 v[80:81], v[82:83], v[118:119]
	v_exp_f32_e32 v129, v94
	v_pk_add_f32 v[80:81], v[80:81], v[80:81] op_sel_hi:[0,1]
	v_add_f32_e32 v83, v206, v128
	v_mov_b32_e32 v82, v207
	v_mov_b32_e32 v121, v81
	v_pk_add_f32 v[80:81], v[82:83], v[120:121]
	v_add_f32_e32 v83, v204, v129
	v_pk_add_f32 v[80:81], v[80:81], v[80:81] op_sel_hi:[0,1]
	v_mov_b32_e32 v82, v205
	v_mov_b32_e32 v123, v81
	v_pk_add_f32 v[80:81], v[82:83], v[122:123]
	v_cvt_pk_bf16_f32 v89, v211, v192
	v_cvt_pk_bf16_f32 v90, v212, v198
	v_cvt_pk_bf16_f32 v91, v213, v196
	v_cvt_pk_bf16_f32 v92, v202, v203
	v_cvt_pk_bf16_f32 v93, v200, v201
	s_nop 0
	v_pk_add_f32 v[80:81], v[80:81], v[80:81] op_sel:[0,1] op_sel_hi:[1,0]
	v_cvt_pk_bf16_f32 v94, v206, v207
	v_cvt_pk_bf16_f32 v95, v204, v205
	v_cvt_pk_bf16_f32 v112, v112, v152
	v_cvt_pk_bf16_f32 v113, v113, v114
	v_cvt_pk_bf16_f32 v114, v124, v84
	s_nop 0
	v_mov_b32_e32 v82, v80
	v_cvt_pk_bf16_f32 v115, v125, v86
	v_cvt_pk_bf16_f32 v116, v126, v116
	v_cvt_pk_bf16_f32 v117, v127, v118
	v_cvt_pk_bf16_f32 v118, v128, v120
	v_cvt_pk_bf16_f32 v119, v129, v122
	s_nop 1
	v_permlane32_swap_b32_e32 v80, v82
	v_permlane32_swap_b32_e32 v88, v90
	v_permlane32_swap_b32_e32 v89, v91
	v_permlane32_swap_b32_e32 v92, v94
	v_permlane32_swap_b32_e32 v93, v95
	v_permlane32_swap_b32_e32 v112, v114
	v_permlane32_swap_b32_e32 v113, v115
	v_permlane32_swap_b32_e32 v116, v118
	v_permlane32_swap_b32_e32 v117, v119
	ds_read_b64_tr_b16 v[84:85], v248 offset:0
	ds_read_b64_tr_b16 v[86:87], v248 offset:0x800
	ds_read_b64_tr_b16 v[120:121], v248 offset:0x1000
	ds_read_b64_tr_b16 v[122:123], v248 offset:0x1800
	ds_read_b64_tr_b16 v[124:125], v248 offset:0x2000
	ds_read_b64_tr_b16 v[126:127], v248 offset:0x2800
	ds_read_b64_tr_b16 v[128:129], v248 offset:0x3000
	ds_read_b64_tr_b16 v[130:131], v248 offset:0x3800
	s_waitcnt lgkmcnt(0)
	s_nop 0
	v_mfma_f32_32x32x16_bf16 v[48:63], v[88:91], v[84:87], v[48:63]
	v_exp_f32_e32 v132, v96
	v_exp_f32_e32 v84, v97
	ds_read_b64_tr_b16 v[96:97], v248 offset:0x200
	v_exp_f32_e32 v133, v98
	v_exp_f32_e32 v86, v99
	ds_read_b64_tr_b16 v[98:99], v248 offset:0xa00
	v_mfma_f32_32x32x16_bf16 v[48:63], v[92:95], v[120:123], v[48:63]
	ds_read_b64_tr_b16 v[120:121], v248 offset:0x1200
	ds_read_b64_tr_b16 v[122:123], v248 offset:0x1a00
	v_mfma_f32_32x32x16_bf16 v[48:63], v[112:115], v[124:127], v[48:63]
	ds_read_b64_tr_b16 v[124:125], v248 offset:0x2200
	ds_read_b64_tr_b16 v[126:127], v248 offset:0x2a00
	v_mfma_f32_32x32x16_bf16 v[48:63], v[116:119], v[128:131], v[48:63]
	ds_read_b64_tr_b16 v[128:129], v248 offset:0x3200
	ds_read_b64_tr_b16 v[130:131], v248 offset:0x3a00
	s_waitcnt lgkmcnt(0)
	v_mfma_f32_32x32x16_bf16 v[32:47], v[88:91], v[96:99], v[32:47]
	ds_read_b64_tr_b16 v[96:97], v248 offset:0x400
	ds_read_b64_tr_b16 v[98:99], v248 offset:0xc00
	v_exp_f32_e32 v134, v100
	v_exp_f32_e32 v135, v102
	v_mfma_f32_32x32x16_bf16 v[32:47], v[92:95], v[120:123], v[32:47]
	v_mfma_f32_32x32x16_bf16 v[32:47], v[112:115], v[124:127], v[32:47]
	v_mfma_f32_32x32x16_bf16 v[32:47], v[116:119], v[128:131], v[32:47]
	v_exp_f32_e32 v128, v101
	ds_read_b64_tr_b16 v[100:101], v248 offset:0x1400
	v_exp_f32_e32 v130, v103
	ds_read_b64_tr_b16 v[102:103], v248 offset:0x1c00
	ds_read_b64_tr_b16 v[120:121], v248 offset:0x2400
	ds_read_b64_tr_b16 v[122:123], v248 offset:0x2c00
	ds_read_b64_tr_b16 v[124:125], v248 offset:0x3400
	ds_read_b64_tr_b16 v[126:127], v248 offset:0x3c00
	s_waitcnt lgkmcnt(0)
	v_mfma_f32_32x32x16_bf16 v[16:31], v[88:91], v[96:99], v[16:31]
	ds_read_b64_tr_b16 v[96:97], v248 offset:0x600
	ds_read_b64_tr_b16 v[98:99], v248 offset:0xe00
	v_exp_f32_e32 v136, v104
	v_exp_f32_e32 v137, v106
	v_mfma_f32_32x32x16_bf16 v[16:31], v[92:95], v[100:103], v[16:31]
	ds_read_b64_tr_b16 v[100:101], v248 offset:0x1600
	ds_read_b64_tr_b16 v[102:103], v248 offset:0x1e00
	v_mfma_f32_32x32x16_bf16 v[16:31], v[112:115], v[120:123], v[16:31]
	v_mfma_f32_32x32x16_bf16 v[16:31], v[116:119], v[124:127], v[16:31]
	v_exp_f32_e32 v124, v105
	ds_read_b64_tr_b16 v[104:105], v248 offset:0x2600
	v_exp_f32_e32 v126, v107
	ds_read_b64_tr_b16 v[106:107], v248 offset:0x2e00
	ds_read_b64_tr_b16 v[120:121], v248 offset:0x3600
	ds_read_b64_tr_b16 v[122:123], v248 offset:0x3e00
	s_waitcnt lgkmcnt(0)
	v_mfma_f32_32x32x16_bf16 v[0:15], v[88:91], v[96:99], v[0:15]
	v_exp_f32_e32 v152, v65
	v_exp_f32_e32 v88, v109
	v_exp_f32_e32 v109, v66
	v_exp_f32_e32 v90, v111
	v_exp_f32_e32 v111, v70
	v_exp_f32_e32 v96, v71
	v_add_f32_e32 v87, v133, v109
	v_mfma_f32_32x32x16_bf16 v[0:15], v[92:95], v[100:103], v[0:15]
	v_exp_f32_e32 v92, v67
	v_exp_f32_e32 v94, v69
	v_exp_f32_e32 v98, v73
	v_add_f32_e32 v131, v135, v111
	v_exp_f32_e32 v100, v75
	v_exp_f32_e32 v102, v77
	v_cvt_pk_bf16_f32 v66, v132, v84
	v_mfma_f32_32x32x16_bf16 v[0:15], v[112:115], v[104:107], v[0:15]
	v_exp_f32_e32 v106, v108
	v_exp_f32_e32 v108, v64
	v_exp_f32_e32 v107, v110
	v_exp_f32_e32 v110, v68
	v_exp_f32_e32 v112, v72
	v_add_f32_e32 v85, v132, v108
	v_pk_add_f32 v[64:65], v[84:85], v[152:153]
	v_add_f32_e32 v129, v134, v110
	v_pk_add_f32 v[64:65], v[64:65], v[64:65] op_sel_hi:[0,1]
	v_mov_b32_e32 v93, v65
	v_pk_add_f32 v[64:65], v[86:87], v[92:93]
	v_exp_f32_e32 v113, v74
	v_pk_add_f32 v[64:65], v[64:65], v[64:65] op_sel_hi:[0,1]
	v_mov_b32_e32 v95, v65
	v_pk_add_f32 v[64:65], v[128:129], v[94:95]
	v_add_f32_e32 v125, v136, v112
	v_pk_add_f32 v[64:65], v[64:65], v[64:65] op_sel_hi:[0,1]
	v_mov_b32_e32 v97, v65
	v_pk_add_f32 v[64:65], v[130:131], v[96:97]
	v_exp_f32_e32 v114, v76
	v_pk_add_f32 v[64:65], v[64:65], v[64:65] op_sel_hi:[0,1]
	v_mov_b32_e32 v99, v65
	v_pk_add_f32 v[64:65], v[124:125], v[98:99]
	v_add_f32_e32 v127, v137, v113
	v_pk_add_f32 v[64:65], v[64:65], v[64:65] op_sel_hi:[0,1]
	v_mov_b32_e32 v101, v65
	v_pk_add_f32 v[64:65], v[126:127], v[100:101]
	v_exp_f32_e32 v115, v78
	v_pk_add_f32 v[64:65], v[64:65], v[64:65] op_sel_hi:[0,1]
	v_exp_f32_e32 v104, v79
	v_add_f32_e32 v89, v106, v114
	v_mov_b32_e32 v103, v65
	v_pk_add_f32 v[64:65], v[88:89], v[102:103]
	v_add_f32_e32 v91, v107, v115
	v_pk_add_f32 v[64:65], v[64:65], v[64:65] op_sel_hi:[0,1]
	v_mov_b32_e32 v105, v65
	v_pk_add_f32 v[64:65], v[90:91], v[104:105]
	v_mfma_f32_32x32x16_bf16 v[0:15], v[116:119], v[120:123], v[0:15]
	v_pk_add_f32 v[64:65], v[64:65], v[64:65] op_sel:[0,1] op_sel_hi:[1,0]
	v_cvt_pk_bf16_f32 v67, v133, v86
	v_cvt_pk_bf16_f32 v68, v134, v128
	v_cvt_pk_bf16_f32 v69, v135, v130
	v_cvt_pk_bf16_f32 v70, v136, v124
	v_cvt_pk_bf16_f32 v71, v137, v126
	s_nop 0
	v_mov_b32_e32 v83, v64
	s_nop 1
	v_permlane32_swap_b32_e32 v64, v83
	v_mov_b32_e32 v81, v64
	v_pk_add_f32 v[64:65], v[80:81], v[82:83]
	v_cvt_pk_bf16_f32 v72, v106, v88
	v_cvt_pk_bf16_f32 v73, v107, v90
	v_cvt_pk_bf16_f32 v74, v108, v152
	v_cvt_pk_bf16_f32 v75, v109, v92
	v_cvt_pk_bf16_f32 v76, v110, v94
	s_nop 0
	v_cmp_ngt_f32_e32 vcc, s59, v65
	v_cmp_ngt_f32_e64 s[2:3], s59, v64
	s_or_b64 s[2:3], s[2:3], vcc
	s_or_b64 s[2:3], s[14:15], s[2:3]
	v_cvt_pk_bf16_f32 v77, v111, v96
	v_cvt_pk_bf16_f32 v78, v112, v98
	v_cvt_pk_bf16_f32 v79, v113, v100
	v_cvt_pk_bf16_f32 v80, v114, v102
	v_cvt_pk_bf16_f32 v81, v115, v104
	v_permlane32_swap_b32_e32 v66, v68
	v_permlane32_swap_b32_e32 v67, v69
	v_permlane32_swap_b32_e32 v70, v72
	v_permlane32_swap_b32_e32 v71, v73
	v_permlane32_swap_b32_e32 v74, v76
	v_permlane32_swap_b32_e32 v75, v77
	v_permlane32_swap_b32_e32 v78, v80
	v_permlane32_swap_b32_e32 v79, v81
	ds_read_b64_tr_b16 v[82:83], v247 offset:0
	ds_read_b64_tr_b16 v[84:85], v247 offset:0x800
	ds_read_b64_tr_b16 v[86:87], v247 offset:0x1000
	ds_read_b64_tr_b16 v[88:89], v247 offset:0x1800
	ds_read_b64_tr_b16 v[90:91], v247 offset:0x2000
	ds_read_b64_tr_b16 v[92:93], v247 offset:0x2800
	ds_read_b64_tr_b16 v[94:95], v247 offset:0x3000
	ds_read_b64_tr_b16 v[96:97], v247 offset:0x3800
	s_waitcnt lgkmcnt(0)
	s_nop 0
	v_mfma_f32_32x32x16_bf16 v[48:63], v[66:69], v[82:85], v[48:63]
	ds_read_b64_tr_b16 v[82:83], v247 offset:0x200
	ds_read_b64_tr_b16 v[84:85], v247 offset:0xa00
	v_mfma_f32_32x32x16_bf16 v[48:63], v[70:73], v[86:89], v[48:63]
	ds_read_b64_tr_b16 v[86:87], v247 offset:0x1200
	ds_read_b64_tr_b16 v[88:89], v247 offset:0x1a00
	v_mfma_f32_32x32x16_bf16 v[48:63], v[74:77], v[90:93], v[48:63]
	ds_read_b64_tr_b16 v[90:91], v247 offset:0x2200
	ds_read_b64_tr_b16 v[92:93], v247 offset:0x2a00
	v_mfma_f32_32x32x16_bf16 v[48:63], v[78:81], v[94:97], v[48:63]
	ds_read_b64_tr_b16 v[94:95], v247 offset:0x3200
	ds_read_b64_tr_b16 v[96:97], v247 offset:0x3a00
	s_waitcnt lgkmcnt(0)
	v_mfma_f32_32x32x16_bf16 v[32:47], v[66:69], v[82:85], v[32:47]
	ds_read_b64_tr_b16 v[82:83], v247 offset:0x400
	ds_read_b64_tr_b16 v[84:85], v247 offset:0xc00
	v_mfma_f32_32x32x16_bf16 v[32:47], v[70:73], v[86:89], v[32:47]
	ds_read_b64_tr_b16 v[86:87], v247 offset:0x1400
	ds_read_b64_tr_b16 v[88:89], v247 offset:0x1c00
	v_mfma_f32_32x32x16_bf16 v[32:47], v[74:77], v[90:93], v[32:47]
	ds_read_b64_tr_b16 v[90:91], v247 offset:0x2400
	ds_read_b64_tr_b16 v[92:93], v247 offset:0x2c00
	v_mfma_f32_32x32x16_bf16 v[32:47], v[78:81], v[94:97], v[32:47]
	ds_read_b64_tr_b16 v[94:95], v247 offset:0x3400
	ds_read_b64_tr_b16 v[96:97], v247 offset:0x3c00
	s_waitcnt lgkmcnt(0)
	v_mfma_f32_32x32x16_bf16 v[16:31], v[66:69], v[82:85], v[16:31]
	ds_read_b64_tr_b16 v[82:83], v247 offset:0x600
	ds_read_b64_tr_b16 v[84:85], v247 offset:0xe00
	v_mfma_f32_32x32x16_bf16 v[16:31], v[70:73], v[86:89], v[16:31]
	ds_read_b64_tr_b16 v[86:87], v247 offset:0x1600
	ds_read_b64_tr_b16 v[88:89], v247 offset:0x1e00
	v_mfma_f32_32x32x16_bf16 v[16:31], v[74:77], v[90:93], v[16:31]
	ds_read_b64_tr_b16 v[90:91], v247 offset:0x2600
	ds_read_b64_tr_b16 v[92:93], v247 offset:0x2e00
	v_mfma_f32_32x32x16_bf16 v[16:31], v[78:81], v[94:97], v[16:31]
	ds_read_b64_tr_b16 v[94:95], v247 offset:0x3600
	ds_read_b64_tr_b16 v[96:97], v247 offset:0x3e00
	s_waitcnt lgkmcnt(0)
	v_mfma_f32_32x32x16_bf16 v[0:15], v[66:69], v[82:85], v[0:15]
	v_mfma_f32_32x32x16_bf16 v[0:15], v[70:73], v[86:89], v[0:15]
	v_mfma_f32_32x32x16_bf16 v[0:15], v[74:77], v[90:93], v[0:15]
	v_mfma_f32_32x32x16_bf16 v[0:15], v[78:81], v[94:97], v[0:15]
	s_setprio 0
	v_and_b32_e32 v247, 0xfffeffff, v247
	v_and_b32_e32 v248, 0xfffeffff, v248
	v_and_b32_e32 v249, 0xfffeffff, v249
	v_and_b32_e32 v250, 0xfffeffff, v250
	v_and_b32_e32 v251, 0xfffeffff, v251
	v_and_b32_e32 v252, 0xfffeffff, v252
	v_and_b32_e32 v231, 0xfffeffff, v231
	v_and_b32_e32 v232, 0xfffeffff, v232
	v_and_b32_e32 v233, 0xfffeffff, v233
	v_cndmask_b32_e64 v66, 0, 1, s[2:3]
	v_cmp_ne_u32_e32 vcc, 0, v66
	s_cmp_lg_u64 vcc, 0
	s_cselect_b64 s[2:3], -1, 0
	v_cmp_eq_u32_e32 vcc, 0, v245
	s_and_b64 s[14:15], vcc, s[2:3]
	s_and_saveexec_b64 s[2:3], s[14:15]
	ds_write_b32 v153, v229 offset:51200
	s_or_b64 exec, exec, s[2:3]
	s_waitcnt vmcnt(0) lgkmcnt(0)
	s_barrier
	ds_read_b32 v66, v153 offset:51200
	s_waitcnt lgkmcnt(0)
	s_barrier
	v_cmp_eq_u32_e32 vcc, 0, v66
	s_cbranch_vccnz .LBB0_861
	v_mbcnt_lo_u32_b32 v0, -1, 0
	v_mbcnt_hi_u32_b32 v0, -1, v0
	v_mov_b64_e32 v[14:15], s[94:95]
	v_add_u32_e32 v35, s33, v0
	v_mov_b32_e32 v33, v153
	v_ashrrev_i32_e32 v0, 1, v35
	v_and_b32_e32 v34, 31, v35
	v_and_b32_e32 v0, 0xffffffe0, v0
	v_ashrrev_i32_e32 v1, 31, v0
	v_or_b32_e32 v152, s8, v34
	v_ashrrev_i32_e32 v188, 3, v35
	v_lshlrev_b32_e32 v16, 3, v35
	v_lshl_add_u64 v[12:13], v[152:153], 0, v[0:1]
	v_and_b32_e32 v0, 56, v16
	v_ashrrev_i32_e32 v189, 31, v188
	v_lshlrev_b32_e32 v32, 1, v0
	v_lshl_add_u64 v[0:1], v[188:189], 0, s[10:11]
	v_ashrrev_i32_e32 v190, 4, v35
	v_mad_u64_u32 v[2:3], s[2:3], v0, s60, v[14:15]
	v_mad_i32_i24 v3, v1, s60, v3
	v_ashrrev_i32_e32 v191, 31, v190
	v_lshl_add_u64 v[0:1], v[2:3], 0, v[32:33]
	v_lshl_add_u64 v[2:3], v[190:191], 0, s[10:11]
	v_mov_b64_e32 v[4:5], s[70:71]
	v_mad_u64_u32 v[4:5], s[2:3], v2, s60, v[4:5]
	v_and_b32_e32 v6, 0x78, v16
	v_mad_i32_i24 v5, v3, s60, v5
	s_mov_b32 s91, s49
	v_lshl_add_u64 v[2:3], v[4:5], 0, s[90:91]
	v_lshlrev_b32_e32 v152, 1, v6
	v_lshl_add_u64 v[8:9], v[2:3], 0, v[152:153]
	global_load_dwordx4 v[0:3], v[0:1], off offset:3200
	s_nop 0
	global_load_dwordx4 v[4:7], v[8:9], off
	v_add_co_u32_e32 v8, vcc, s58, v8
	v_mad_u64_u32 v[14:15], s[2:3], v12, s60, v[14:15]
	s_nop 0
	v_addc_co_u32_e32 v9, vcc, 0, v9, vcc
	global_load_dwordx4 v[8:11], v[8:9], off
	v_lshrrev_b32_e32 v17, 1, v35
	v_mad_i32_i24 v15, v13, s60, v15
	v_and_b32_e32 v186, 16, v17
	v_mov_b32_e32 v187, v153
	v_lshl_add_u64 v[12:13], v[14:15], 0, v[186:187]
	global_load_dwordx4 v[116:119], v[12:13], off offset:2176
	global_load_dwordx4 v[120:123], v[12:13], off offset:2208
	global_load_dwordx4 v[124:127], v[12:13], off offset:2240
	global_load_dwordx4 v[112:115], v[12:13], off offset:2272
	v_and_b32_e32 v19, 0xfffff0, v190
	v_lshlrev_b32_e32 v20, 1, v190
	v_lshrrev_b32_e32 v21, 1, v190
	v_and_b32_e32 v23, 3, v190
	v_add_u32_e32 v24, 32, v190
	v_and_b32_e32 v14, 0x70, v35
	v_lshlrev_b32_e32 v18, 7, v188
	v_bfe_u32 v22, v16, 5, 2
	v_and_b32_e32 v33, 0x70, v16
	v_and_or_b32 v16, v20, 8, v19
	v_and_or_b32 v19, v21, 4, v23
	v_and_b32_e32 v20, 0xfffff0, v24
	v_lshlrev_b32_e32 v21, 1, v24
	v_lshl_add_u32 v40, v34, 7, 0
	v_bitop3_b32 v17, v17, v33, 16 bitop3:0x6c
	v_bitop3_b32 v14, v32, v18, v14 bitop3:0xde
	v_lshrrev_b32_e32 v16, 1, v16
	v_lshlrev_b32_e32 v18, 6, v19
	v_and_or_b32 v19, v21, 8, v20
	v_add_u32_e32 v197, v40, v17
	v_or_b32_e32 v16, v16, v22
	v_lshrrev_b32_e32 v17, 1, v19
	v_lshlrev_b32_e32 v15, 4, v35
	v_add_u32_e32 v198, 0, v14
	v_lshlrev_b32_e32 v14, 9, v16
	v_or_b32_e32 v16, v17, v22
	v_and_b32_e32 v15, 48, v15
	v_lshlrev_b32_e32 v12, 9, v16
	v_or3_b32 v14, v14, v18, v15
	v_or3_b32 v12, v12, v18, v15
	v_add_u32_e32 v199, 0, v14
	v_add_u32_e32 v200, 0, v12
	v_bitop3_b32 v20, v186, v33, 32 bitop3:0x36
	v_add_u32_e32 v201, v40, v20
	v_bitop3_b32 v41, v186, v33, 64 bitop3:0x36
	v_add_u32_e32 v202, v40, v41
	v_bitop3_b32 v33, v186, v33, s88 bitop3:0x36
	v_add_u32_e32 v203, v40, v33
	s_waitcnt vmcnt(6)
	ds_write_b128 v198, v[0:3] offset:32768
	s_waitcnt vmcnt(5)
	ds_write_b128 v199, v[4:7]
	s_waitcnt vmcnt(4)
	ds_write_b128 v200, v[8:11]
	s_waitcnt lgkmcnt(0)
	s_barrier
	ds_read_b128 v[0:3], v197 offset:32768
	ds_read_b128 v[16:19], v197 offset:36864
	ds_read_b128 v[36:39], v201 offset:32768
	s_waitcnt vmcnt(3) lgkmcnt(2)
	v_mfma_f32_32x32x16_bf16 v[0:15], v[0:3], v[116:119], 0
	s_waitcnt vmcnt(2) lgkmcnt(0)
	v_mfma_f32_32x32x16_bf16 v[0:15], v[36:39], v[120:123], v[0:15]
	ds_read_b128 v[36:39], v201 offset:36864
	v_mfma_f32_32x32x16_bf16 v[16:31], v[16:19], v[116:119], 0
	s_waitcnt lgkmcnt(0)
	v_mfma_f32_32x32x16_bf16 v[16:31], v[36:39], v[120:123], v[16:31]
	ds_read_b128 v[36:39], v202 offset:32768
	s_waitcnt vmcnt(1) lgkmcnt(0)
	v_mfma_f32_32x32x16_bf16 v[0:15], v[36:39], v[124:127], v[0:15]
	ds_read_b128 v[36:39], v202 offset:36864
	s_waitcnt lgkmcnt(0)
	v_mfma_f32_32x32x16_bf16 v[16:31], v[36:39], v[124:127], v[16:31]
	ds_read_b128 v[36:39], v203 offset:32768
	s_waitcnt vmcnt(0) lgkmcnt(0)
	v_mfma_f32_32x32x16_bf16 v[0:15], v[36:39], v[112:115], v[0:15]
	ds_read_b128 v[36:39], v203 offset:36864
	s_waitcnt lgkmcnt(0)
	v_mfma_f32_32x32x16_bf16 v[16:31], v[36:39], v[112:115], v[16:31]
	s_nop 8
	v_max_f32_e32 v33, v1, v1
	v_max_f32_e32 v36, v0, v0
	v_max_f32_e32 v33, v36, v33
	v_max3_f32 v33, v33, v2, v3
	v_max3_f32 v33, v33, v4, v5
	v_max3_f32 v33, v33, v6, v7
	v_max3_f32 v33, v33, v8, v9
	v_max3_f32 v33, v33, v10, v11
	v_max3_f32 v33, v33, v12, v13
	v_max3_f32 v33, v33, v14, v15
	v_max3_f32 v33, v33, v16, v17
	v_max3_f32 v33, v33, v18, v19
	v_max3_f32 v33, v33, v20, v21
	v_max3_f32 v33, v33, v22, v23
	v_max3_f32 v33, v33, v24, v25
	v_max3_f32 v33, v33, v26, v27
	v_max3_f32 v33, v33, v28, v29
	v_max3_f32 v33, v33, v30, v31
	v_mov_b32_e32 v36, v33
	s_nop 1
	v_permlane32_swap_b32_e32 v33, v36
	v_max_f32_e32 v36, v36, v36
	v_max_f32_e32 v33, v33, v33
	v_max_f32_e32 v33, v33, v36
	v_add_f32_e32 v36, 0x7149f2ca, v33
	v_cmp_ge_f32_e32 vcc, s66, v36
	s_cmp_eq_u64 vcc, exec
	s_cbranch_scc0 .LBB0_867
	v_mov_b32_e32 v184, 0xf149f2ca
	v_mov_b32_e32 v204, 1.0
